# strategy 9 (7.11): K-loop back-edge SALU block (counter/address bumps + compare) moved ahead of the closing barrier in all four GEMM loops, on top of the no-setprio kernel
# speedup vs baseline: 1.0010x; 1.0010x over previous
; #define PG8_STAGE(bufoff, gbase, voff) do { _Pragma("unroll") for (int _i = 0; _i < 2; ++_i) \
;         __builtin_amdgcn_global_load_lds((const unsigned*)((const char*)(gbase) + (voff)[_i]), (PG8_LAS unsigned*)(lds + (bufoff) + ldsw + _i * 8192), 16, 0, 0); } while (0)
; #define PG8_LDA(dst, b, h) do { _Pragma("unroll") for (int m = 0; m < 4; ++m) _Pragma("unroll") for (int k = 0; k < 2; ++k) dst[m][k] = *(const PG8_LAS bf16x8*)(lds + PG8_SA(b, h) + aoff + m * 2048 + k * 1024); } while (0)
; #define PG8_LDB(dst, b, h) do { _Pragma("unroll") for (int n = 0; n < 2; ++n) _Pragma("unroll") for (int k = 0; k < 2; ++k) dst[n][k] = *(const PG8_LAS bf16x8*)(lds + PG8_SB(b, h) + boff + n * 2048 + k * 1024); } while (0)
; template <class Epi, class Sched, bool ALIGN_EPI = false, bool SP2 = false>
; __device__ __forceinline__ void gemm_phase(PG8_LAS unsigned char* lds, const Gemm g, const Sched& S, const Epi& E) {
;     ...
;         for (int t = 0; t < nt; t += 2) {
;             const bool last = (t == nt - 2);
;             const char* a1 = cA + (size_t)(t + 1) * kstep;
;             const char* a2 = last ? nA : cA + (size_t)(t + 2) * kstep; const char* b2 = last ? nB : cB + (size_t)(t + 2) * kstep;
;             const char* a3 = a2 + kstep; const char* b3 = b2 + kstep;
;             if (last && has_next) S.a_ready(nxt);
;             if constexpr (SP2) {
;             PG8_LDB(B0, 0, 0); PG8_LDB(B1, 0, 1); PG8_SCHED; PG8_LDA(At, 0, 0); PG8_STAGE(PG8_SA(1, 1), a1 + hstep, voffA);
;             PG8_WAIT_V(8); PG8_WAIT_L(0); PG8_BAR; PG8_MMA(0, 0, At, B0); PG8_MMA(0, 1, At, B1); PG8_BAR; PG8_SCHED;
;             PG8_LDA(At, 0, 1); PG8_STAGE(PG8_SB(0, 0), b2, voffB); PG8_STAGE(PG8_SB(0, 1), b2 + hstep, voffB); PG8_STAGE(PG8_SA(0, 0), a2, voffA);
;             PG8_WAIT_V(8); PG8_WAIT_L(0); PG8_BAR; PG8_MMA(1, 0, At, B0); PG8_MMA(1, 1, At, B1); PG8_BAR; PG8_SCHED;
;             PG8_LDB(B0, 1, 0); PG8_LDB(B1, 1, 1); PG8_SCHED; PG8_LDA(At, 1, 0); PG8_STAGE(PG8_SA(0, 1), a2 + hstep, voffA);
;             PG8_WAIT_V(8); PG8_WAIT_L(0); PG8_BAR; PG8_MMA(0, 0, At, B0); PG8_MMA(0, 1, At, B1); PG8_BAR; PG8_SCHED;
;             PG8_LDA(At, 1, 1); PG8_STAGE(PG8_SB(1, 0), b3, voffB); PG8_STAGE(PG8_SB(1, 1), b3 + hstep, voffB); PG8_STAGE(PG8_SA(1, 0), a3, voffA);
;             PG8_WAIT_V(8); PG8_WAIT_L(0); PG8_BAR; PG8_MMA(1, 0, At, B0); PG8_MMA(1, 1, At, B1); PG8_BAR; PG8_SCHED;
.LBB0_68:
	ds_read_b128 v[128:131], v203
	ds_read_b128 v[132:135], v203 offset:1024
	ds_read_b128 v[136:139], v203 offset:2048
	ds_read_b128 v[140:143], v203 offset:3072
	ds_read_b128 v[144:147], v204
	ds_read_b128 v[148:151], v204 offset:1024
	ds_read_b128 v[180:183], v204 offset:2048
	ds_read_b128 v[184:187], v204 offset:3072
	s_add_u32 s30, s82, 0xfff80080
	s_addc_u32 s31, s83, -1
	s_cmp_eq_u32 s29, 28
	s_cselect_b32 s87, s1, s31
	s_cselect_b32 s86, s75, s30
	s_cselect_b32 s85, s73, vcc_hi
	s_cselect_b32 s84, s81, vcc_lo
	s_add_i32 m0, s94, 0xc000
	ds_read_b128 v[206:209], v205
	ds_read_b128 v[210:213], v205 offset:1024
	ds_read_b128 v[214:217], v205 offset:2048
	ds_read_b128 v[218:221], v205 offset:3072
	ds_read_b128 v[222:225], v205 offset:4096
	ds_read_b128 v[226:229], v205 offset:5120
	ds_read_b128 v[230:233], v205 offset:6144
	ds_read_b128 v[234:237], v205 offset:7168
	global_load_lds_dwordx4 v170, s[82:83]
	s_add_i32 m0, s94, 0xe000
	s_nop 0
	global_load_lds_dwordx4 v172, s[82:83]
	s_waitcnt vmcnt(8)
	s_waitcnt lgkmcnt(0)
	s_barrier
	s_waitcnt lgkmcnt(0)
	v_mfma_f32_16x16x32_bf16 v[124:127], v[128:131], v[206:209], v[124:127]
	v_mfma_f32_16x16x32_bf16 v[120:123], v[136:139], v[206:209], v[120:123]
	v_mfma_f32_16x16x32_bf16 v[116:119], v[128:131], v[214:217], v[116:119]
	v_mfma_f32_16x16x32_bf16 v[112:115], v[136:139], v[214:217], v[112:115]
	v_mfma_f32_16x16x32_bf16 v[108:111], v[128:131], v[222:225], v[108:111]
	v_mfma_f32_16x16x32_bf16 v[104:107], v[136:139], v[222:225], v[104:107]
	v_mfma_f32_16x16x32_bf16 v[100:103], v[128:131], v[230:233], v[100:103]
	v_mfma_f32_16x16x32_bf16 v[96:99], v[136:139], v[230:233], v[96:99]
	v_mfma_f32_16x16x32_bf16 v[124:127], v[132:135], v[210:213], v[124:127]
	v_mfma_f32_16x16x32_bf16 v[120:123], v[140:143], v[210:213], v[120:123]
	v_mfma_f32_16x16x32_bf16 v[116:119], v[132:135], v[218:221], v[116:119]
	v_mfma_f32_16x16x32_bf16 v[112:115], v[140:143], v[218:221], v[112:115]
	v_mfma_f32_16x16x32_bf16 v[108:111], v[132:135], v[226:229], v[108:111]
	v_mfma_f32_16x16x32_bf16 v[104:107], v[140:143], v[226:229], v[104:107]
	v_mfma_f32_16x16x32_bf16 v[100:103], v[132:135], v[234:237], v[100:103]
	v_mfma_f32_16x16x32_bf16 v[96:99], v[140:143], v[234:237], v[96:99]
	v_mfma_f32_16x16x32_bf16 v[68:71], v[144:147], v[206:209], v[68:71]
	v_mfma_f32_16x16x32_bf16 v[64:67], v[180:183], v[206:209], v[64:67]
	v_mfma_f32_16x16x32_bf16 v[52:55], v[144:147], v[214:217], v[52:55]
	v_mfma_f32_16x16x32_bf16 v[48:51], v[180:183], v[214:217], v[48:51]
	v_mfma_f32_16x16x32_bf16 v[44:47], v[144:147], v[222:225], v[44:47]
	v_mfma_f32_16x16x32_bf16 v[40:43], v[180:183], v[222:225], v[40:43]
	v_mfma_f32_16x16x32_bf16 v[36:39], v[144:147], v[230:233], v[36:39]
	v_mfma_f32_16x16x32_bf16 v[32:35], v[180:183], v[230:233], v[32:35]
	v_mfma_f32_16x16x32_bf16 v[68:71], v[148:151], v[210:213], v[68:71]
	v_mfma_f32_16x16x32_bf16 v[64:67], v[184:187], v[210:213], v[64:67]
	v_mfma_f32_16x16x32_bf16 v[52:55], v[148:151], v[218:221], v[52:55]
	v_mfma_f32_16x16x32_bf16 v[48:51], v[184:187], v[218:221], v[48:51]
	v_mfma_f32_16x16x32_bf16 v[44:47], v[148:151], v[226:229], v[44:47]
	v_mfma_f32_16x16x32_bf16 v[40:43], v[184:187], v[226:229], v[40:43]
	v_mfma_f32_16x16x32_bf16 v[36:39], v[148:151], v[234:237], v[36:39]
	v_mfma_f32_16x16x32_bf16 v[32:35], v[184:187], v[234:237], v[32:35]
	s_barrier
	s_add_i32 s30, s47, s92
	s_mov_b32 m0, s30
	ds_read_b128 v[206:209], v205 offset:16384
	ds_read_b128 v[210:213], v205 offset:17408
	ds_read_b128 v[214:217], v205 offset:18432
	ds_read_b128 v[218:221], v205 offset:19456
	ds_read_b128 v[222:225], v205 offset:20480
	ds_read_b128 v[226:229], v205 offset:21504
	ds_read_b128 v[230:233], v205 offset:22528
	ds_read_b128 v[234:237], v205 offset:23552
	global_load_lds_dwordx4 v158, s[84:85]
	s_add_i32 m0, s30, 0x2000
	s_add_u32 s30, s84, 0x80000
	s_addc_u32 s31, s85, 0
	s_add_i32 s89, s33, s92
	global_load_lds_dwordx4 v154, s[84:85]
	s_mov_b32 m0, s89
	s_nop 0
	global_load_lds_dwordx4 v158, s[30:31]
	s_add_i32 m0, s89, 0x2000
	s_nop 0
	global_load_lds_dwordx4 v154, s[30:31]
	s_mov_b32 m0, s94
	s_nop 0
	global_load_lds_dwordx4 v160, s[86:87]
	s_mov_b32 m0, s95
	s_nop 0
	global_load_lds_dwordx4 v156, s[86:87]
	s_waitcnt vmcnt(8)
	s_waitcnt lgkmcnt(0)
	s_barrier
	s_waitcnt lgkmcnt(0)
	v_mfma_f32_16x16x32_bf16 v[92:95], v[128:131], v[206:209], v[92:95]
	v_mfma_f32_16x16x32_bf16 v[88:91], v[136:139], v[206:209], v[88:91]
	v_mfma_f32_16x16x32_bf16 v[84:87], v[128:131], v[214:217], v[84:87]
	v_mfma_f32_16x16x32_bf16 v[80:83], v[136:139], v[214:217], v[80:83]
	v_mfma_f32_16x16x32_bf16 v[76:79], v[128:131], v[222:225], v[76:79]
	v_mfma_f32_16x16x32_bf16 v[72:75], v[136:139], v[222:225], v[72:75]
	v_mfma_f32_16x16x32_bf16 v[60:63], v[128:131], v[230:233], v[60:63]
	v_mfma_f32_16x16x32_bf16 v[56:59], v[136:139], v[230:233], v[56:59]
	v_mfma_f32_16x16x32_bf16 v[92:95], v[132:135], v[210:213], v[92:95]
	v_mfma_f32_16x16x32_bf16 v[88:91], v[140:143], v[210:213], v[88:91]
	v_mfma_f32_16x16x32_bf16 v[84:87], v[132:135], v[218:221], v[84:87]
	v_mfma_f32_16x16x32_bf16 v[80:83], v[140:143], v[218:221], v[80:83]
	v_mfma_f32_16x16x32_bf16 v[76:79], v[132:135], v[226:229], v[76:79]
	v_mfma_f32_16x16x32_bf16 v[72:75], v[140:143], v[226:229], v[72:75]
	v_mfma_f32_16x16x32_bf16 v[60:63], v[132:135], v[234:237], v[60:63]
	v_mfma_f32_16x16x32_bf16 v[56:59], v[140:143], v[234:237], v[56:59]
	v_mfma_f32_16x16x32_bf16 v[28:31], v[144:147], v[206:209], v[28:31]
	v_mfma_f32_16x16x32_bf16 v[24:27], v[180:183], v[206:209], v[24:27]
	v_mfma_f32_16x16x32_bf16 v[20:23], v[144:147], v[214:217], v[20:23]
	v_mfma_f32_16x16x32_bf16 v[16:19], v[180:183], v[214:217], v[16:19]
	v_mfma_f32_16x16x32_bf16 v[12:15], v[144:147], v[222:225], v[12:15]
	v_mfma_f32_16x16x32_bf16 v[8:11], v[180:183], v[222:225], v[8:11]
	v_mfma_f32_16x16x32_bf16 v[4:7], v[144:147], v[230:233], v[4:7]
	v_mfma_f32_16x16x32_bf16 v[0:3], v[180:183], v[230:233], v[0:3]
	v_mfma_f32_16x16x32_bf16 v[28:31], v[148:151], v[210:213], v[28:31]
	v_mfma_f32_16x16x32_bf16 v[24:27], v[184:187], v[210:213], v[24:27]
	v_mfma_f32_16x16x32_bf16 v[20:23], v[148:151], v[218:221], v[20:23]
	v_mfma_f32_16x16x32_bf16 v[16:19], v[184:187], v[218:221], v[16:19]
	v_mfma_f32_16x16x32_bf16 v[12:15], v[148:151], v[226:229], v[12:15]
	v_mfma_f32_16x16x32_bf16 v[8:11], v[184:187], v[226:229], v[8:11]
	v_mfma_f32_16x16x32_bf16 v[4:7], v[148:151], v[234:237], v[4:7]
	v_mfma_f32_16x16x32_bf16 v[0:3], v[184:187], v[234:237], v[0:3]
	s_barrier
; #define PG8_STAGE(bufoff, gbase, voff) do { _Pragma("unroll") for (int _i = 0; _i < 2; ++_i) \
;         __builtin_amdgcn_global_load_lds((const unsigned*)((const char*)(gbase) + (voff)[_i]), (PG8_LAS unsigned*)(lds + (bufoff) + ldsw + _i * 8192), 16, 0, 0); } while (0)
; #define PG8_LDA(dst, b, h) do { _Pragma("unroll") for (int m = 0; m < 4; ++m) _Pragma("unroll") for (int k = 0; k < 2; ++k) dst[m][k] = *(const PG8_LAS bf16x8*)(lds + PG8_SA(b, h) + aoff + m * 2048 + k * 1024); } while (0)
; #define PG8_LDB(dst, b, h) do { _Pragma("unroll") for (int n = 0; n < 2; ++n) _Pragma("unroll") for (int k = 0; k < 2; ++k) dst[n][k] = *(const PG8_LAS bf16x8*)(lds + PG8_SB(b, h) + boff + n * 2048 + k * 1024); } while (0)
; template <class Epi, class Sched, bool ALIGN_EPI = false, bool SP2 = false>
; __device__ __forceinline__ void gemm_phase(PG8_LAS unsigned char* lds, const Gemm g, const Sched& S, const Epi& E) {
;     ...
;         for (int t = 0; t < nt; t += 2) {
;             const bool last = (t == nt - 2);
;             const char* a1 = cA + (size_t)(t + 1) * kstep;
;             const char* a2 = last ? nA : cA + (size_t)(t + 2) * kstep; const char* b2 = last ? nB : cB + (size_t)(t + 2) * kstep;
;             const char* a3 = a2 + kstep; const char* b3 = b2 + kstep;
;             if (last && has_next) S.a_ready(nxt);
;             if constexpr (SP2) {
;             PG8_LDB(B0, 0, 0); PG8_LDB(B1, 0, 1); PG8_SCHED; PG8_LDA(At, 0, 0); PG8_STAGE(PG8_SA(1, 1), a1 + hstep, voffA);
;             PG8_WAIT_V(8); PG8_WAIT_L(0); PG8_BAR; PG8_MMA(0, 0, At, B0); PG8_MMA(0, 1, At, B1); PG8_BAR; PG8_SCHED;
;             PG8_LDA(At, 0, 1); PG8_STAGE(PG8_SB(0, 0), b2, voffB); PG8_STAGE(PG8_SB(0, 1), b2 + hstep, voffB); PG8_STAGE(PG8_SA(0, 0), a2, voffA);
;             PG8_WAIT_V(8); PG8_WAIT_L(0); PG8_BAR; PG8_MMA(1, 0, At, B0); PG8_MMA(1, 1, At, B1); PG8_BAR; PG8_SCHED;
;             PG8_LDB(B0, 1, 0); PG8_LDB(B1, 1, 1); PG8_SCHED; PG8_LDA(At, 1, 0); PG8_STAGE(PG8_SA(0, 1), a2 + hstep, voffA);
;             PG8_WAIT_V(8); PG8_WAIT_L(0); PG8_BAR; PG8_MMA(0, 0, At, B0); PG8_MMA(0, 1, At, B1); PG8_BAR; PG8_SCHED;
;             PG8_LDA(At, 1, 1); PG8_STAGE(PG8_SB(1, 0), b3, voffB); PG8_STAGE(PG8_SB(1, 1), b3 + hstep, voffB); PG8_STAGE(PG8_SA(1, 0), a3, voffA);
;             PG8_WAIT_V(8); PG8_WAIT_L(0); PG8_BAR; PG8_MMA(1, 0, At, B0); PG8_MMA(1, 1, At, B1); PG8_BAR; PG8_SCHED;
	s_add_i32 s89, 0, 0x18000
	s_add_i32 s54, 0, 0x1c000
	v_add_u32_e32 v140, s89, v190
	v_add_u32_e32 v162, s54, v190
	ds_read_b128 v[128:131], v140
	ds_read_b128 v[132:135], v140 offset:1024
	ds_read_b128 v[136:139], v140 offset:2048
	ds_read_b128 v[140:143], v140 offset:3072
	ds_read_b128 v[144:147], v162
	ds_read_b128 v[148:151], v162 offset:1024
	ds_read_b128 v[180:183], v162 offset:2048
	ds_read_b128 v[184:187], v162 offset:3072
	s_add_u32 s30, s86, 0x80000
	s_addc_u32 s31, s87, 0
	s_mov_b32 m0, s96
	ds_read_b128 v[206:209], v205 offset:32768
	ds_read_b128 v[210:213], v205 offset:33792
	ds_read_b128 v[214:217], v205 offset:34816
	ds_read_b128 v[218:221], v205 offset:35840
	ds_read_b128 v[222:225], v205 offset:36864
	ds_read_b128 v[226:229], v205 offset:37888
	ds_read_b128 v[230:233], v205 offset:38912
	ds_read_b128 v[234:237], v205 offset:39936
	global_load_lds_dwordx4 v160, s[30:31]
	s_mov_b32 m0, s97
	s_nop 0
	global_load_lds_dwordx4 v156, s[30:31]
	s_waitcnt vmcnt(8)
	s_waitcnt lgkmcnt(0)
	s_barrier
	s_waitcnt lgkmcnt(0)
	v_mfma_f32_16x16x32_bf16 v[124:127], v[128:131], v[206:209], v[124:127]
	v_mfma_f32_16x16x32_bf16 v[120:123], v[136:139], v[206:209], v[120:123]
	v_mfma_f32_16x16x32_bf16 v[116:119], v[128:131], v[214:217], v[116:119]
	v_mfma_f32_16x16x32_bf16 v[112:115], v[136:139], v[214:217], v[112:115]
	v_mfma_f32_16x16x32_bf16 v[108:111], v[128:131], v[222:225], v[108:111]
	v_mfma_f32_16x16x32_bf16 v[104:107], v[136:139], v[222:225], v[104:107]
	v_mfma_f32_16x16x32_bf16 v[100:103], v[128:131], v[230:233], v[100:103]
	v_mfma_f32_16x16x32_bf16 v[96:99], v[136:139], v[230:233], v[96:99]
	v_mfma_f32_16x16x32_bf16 v[124:127], v[132:135], v[210:213], v[124:127]
	v_mfma_f32_16x16x32_bf16 v[120:123], v[140:143], v[210:213], v[120:123]
	v_mfma_f32_16x16x32_bf16 v[116:119], v[132:135], v[218:221], v[116:119]
	v_mfma_f32_16x16x32_bf16 v[112:115], v[140:143], v[218:221], v[112:115]
	v_mfma_f32_16x16x32_bf16 v[108:111], v[132:135], v[226:229], v[108:111]
	v_mfma_f32_16x16x32_bf16 v[104:107], v[140:143], v[226:229], v[104:107]
	v_mfma_f32_16x16x32_bf16 v[100:103], v[132:135], v[234:237], v[100:103]
	v_mfma_f32_16x16x32_bf16 v[96:99], v[140:143], v[234:237], v[96:99]
	v_mfma_f32_16x16x32_bf16 v[68:71], v[144:147], v[206:209], v[68:71]
	v_mfma_f32_16x16x32_bf16 v[64:67], v[180:183], v[206:209], v[64:67]
	v_mfma_f32_16x16x32_bf16 v[52:55], v[144:147], v[214:217], v[52:55]
	v_mfma_f32_16x16x32_bf16 v[48:51], v[180:183], v[214:217], v[48:51]
	v_mfma_f32_16x16x32_bf16 v[44:47], v[144:147], v[222:225], v[44:47]
	v_mfma_f32_16x16x32_bf16 v[40:43], v[180:183], v[222:225], v[40:43]
	v_mfma_f32_16x16x32_bf16 v[36:39], v[144:147], v[230:233], v[36:39]
	v_mfma_f32_16x16x32_bf16 v[32:35], v[180:183], v[230:233], v[32:35]
	v_mfma_f32_16x16x32_bf16 v[68:71], v[148:151], v[210:213], v[68:71]
	v_mfma_f32_16x16x32_bf16 v[64:67], v[184:187], v[210:213], v[64:67]
	v_mfma_f32_16x16x32_bf16 v[52:55], v[148:151], v[218:221], v[52:55]
	v_mfma_f32_16x16x32_bf16 v[48:51], v[184:187], v[218:221], v[48:51]
	v_mfma_f32_16x16x32_bf16 v[44:47], v[148:151], v[226:229], v[44:47]
	v_mfma_f32_16x16x32_bf16 v[40:43], v[184:187], v[226:229], v[40:43]
	v_mfma_f32_16x16x32_bf16 v[36:39], v[148:151], v[234:237], v[36:39]
	v_mfma_f32_16x16x32_bf16 v[32:35], v[184:187], v[234:237], v[32:35]
	s_barrier
	s_add_i32 s30, s89, s92
	s_mov_b32 m0, s30
	ds_read_b128 v[206:209], v205 offset:49152
	ds_read_b128 v[210:213], v205 offset:50176
	ds_read_b128 v[214:217], v205 offset:51200
	ds_read_b128 v[218:221], v205 offset:52224
	ds_read_b128 v[222:225], v205 offset:53248
	ds_read_b128 v[226:229], v205 offset:54272
	ds_read_b128 v[230:233], v205 offset:55296
	ds_read_b128 v[234:237], v205 offset:56320
	s_add_u32 s62, s84, 0x80
	s_addc_u32 s63, s85, 0
	global_load_lds_dwordx4 v158, s[62:63]
	s_add_i32 m0, s30, 0x2000
	s_add_u32 s30, s84, 0x80080
	s_addc_u32 s31, s85, 0
	s_add_i32 s54, s54, s92
	global_load_lds_dwordx4 v154, s[62:63]
	s_mov_b32 m0, s54
	s_nop 0
	global_load_lds_dwordx4 v158, s[30:31]
	s_add_i32 m0, s54, 0x2000
	s_nop 0
	global_load_lds_dwordx4 v154, s[30:31]
	s_mov_b32 m0, s88
	s_nop 0
	s_add_u32 s62, s86, 0x80
	s_addc_u32 s63, s87, 0
	global_load_lds_dwordx4 v160, s[62:63]
	s_mov_b32 m0, s46
	s_nop 0
	global_load_lds_dwordx4 v156, s[62:63]
	s_waitcnt vmcnt(8)
	s_waitcnt lgkmcnt(0)
	s_barrier
	s_waitcnt lgkmcnt(0)
	v_mfma_f32_16x16x32_bf16 v[92:95], v[128:131], v[206:209], v[92:95]
	v_mfma_f32_16x16x32_bf16 v[88:91], v[136:139], v[206:209], v[88:91]
	v_mfma_f32_16x16x32_bf16 v[84:87], v[128:131], v[214:217], v[84:87]
	v_mfma_f32_16x16x32_bf16 v[80:83], v[136:139], v[214:217], v[80:83]
	v_mfma_f32_16x16x32_bf16 v[76:79], v[128:131], v[222:225], v[76:79]
	v_mfma_f32_16x16x32_bf16 v[72:75], v[136:139], v[222:225], v[72:75]
	v_mfma_f32_16x16x32_bf16 v[60:63], v[128:131], v[230:233], v[60:63]
	v_mfma_f32_16x16x32_bf16 v[56:59], v[136:139], v[230:233], v[56:59]
	v_mfma_f32_16x16x32_bf16 v[92:95], v[132:135], v[210:213], v[92:95]
	v_mfma_f32_16x16x32_bf16 v[88:91], v[140:143], v[210:213], v[88:91]
	v_mfma_f32_16x16x32_bf16 v[84:87], v[132:135], v[218:221], v[84:87]
	v_mfma_f32_16x16x32_bf16 v[80:83], v[140:143], v[218:221], v[80:83]
	v_mfma_f32_16x16x32_bf16 v[76:79], v[132:135], v[226:229], v[76:79]
	v_mfma_f32_16x16x32_bf16 v[72:75], v[140:143], v[226:229], v[72:75]
	v_mfma_f32_16x16x32_bf16 v[60:63], v[132:135], v[234:237], v[60:63]
	v_mfma_f32_16x16x32_bf16 v[56:59], v[140:143], v[234:237], v[56:59]
	v_mfma_f32_16x16x32_bf16 v[28:31], v[144:147], v[206:209], v[28:31]
	v_mfma_f32_16x16x32_bf16 v[24:27], v[180:183], v[206:209], v[24:27]
	v_mfma_f32_16x16x32_bf16 v[20:23], v[144:147], v[214:217], v[20:23]
	v_mfma_f32_16x16x32_bf16 v[16:19], v[180:183], v[214:217], v[16:19]
	v_mfma_f32_16x16x32_bf16 v[12:15], v[144:147], v[222:225], v[12:15]
	v_mfma_f32_16x16x32_bf16 v[8:11], v[180:183], v[222:225], v[8:11]
	v_mfma_f32_16x16x32_bf16 v[4:7], v[144:147], v[230:233], v[4:7]
	v_mfma_f32_16x16x32_bf16 v[0:3], v[180:183], v[230:233], v[0:3]
	v_mfma_f32_16x16x32_bf16 v[28:31], v[148:151], v[210:213], v[28:31]
	v_mfma_f32_16x16x32_bf16 v[24:27], v[184:187], v[210:213], v[24:27]
	v_mfma_f32_16x16x32_bf16 v[20:23], v[148:151], v[218:221], v[20:23]
	v_mfma_f32_16x16x32_bf16 v[16:19], v[184:187], v[218:221], v[16:19]
	v_mfma_f32_16x16x32_bf16 v[12:15], v[148:151], v[226:229], v[12:15]
	v_mfma_f32_16x16x32_bf16 v[8:11], v[184:187], v[226:229], v[8:11]
	v_mfma_f32_16x16x32_bf16 v[4:7], v[148:151], v[234:237], v[4:7]
	v_mfma_f32_16x16x32_bf16 v[0:3], v[184:187], v[234:237], v[0:3]
	s_add_i32 s29, s29, 2
	s_add_u32 s82, s82, 0x100
	s_addc_u32 s83, s83, 0
	s_add_u32 vcc_lo, vcc_lo, 0x100
	s_addc_u32 vcc_hi, vcc_hi, 0
	s_cmp_gt_u32 s29, 29
	s_barrier
	s_cbranch_scc0 .LBB0_68
	s_and_b64 vcc, exec, s[64:65]
	s_cbranch_vccz .LBB0_71
	s_barrier

; #define PG8_STAGE(bufoff, gbase, voff) do { _Pragma("unroll") for (int _i = 0; _i < 2; ++_i) \
;         __builtin_amdgcn_global_load_lds((const unsigned*)((const char*)(gbase) + (voff)[_i]), (PG8_LAS unsigned*)(lds + (bufoff) + ldsw + _i * 8192), 16, 0, 0); } while (0)
; #define PG8_LDA(dst, b, h) do { _Pragma("unroll") for (int m = 0; m < 4; ++m) _Pragma("unroll") for (int k = 0; k < 2; ++k) dst[m][k] = *(const PG8_LAS bf16x8*)(lds + PG8_SA(b, h) + aoff + m * 2048 + k * 1024); } while (0)
; #define PG8_LDB(dst, b, h) do { _Pragma("unroll") for (int n = 0; n < 2; ++n) _Pragma("unroll") for (int k = 0; k < 2; ++k) dst[n][k] = *(const PG8_LAS bf16x8*)(lds + PG8_SB(b, h) + boff + n * 2048 + k * 1024); } while (0)
; template <class Epi, class Sched, bool ALIGN_EPI = false, bool SP2 = false>
; __device__ __forceinline__ void gemm_phase(PG8_LAS unsigned char* lds, const Gemm g, const Sched& S, const Epi& E) {
;     ...
;         for (int t = 0; t < nt; t += 2) {
;             const bool last = (t == nt - 2);
;             const char* a1 = cA + (size_t)(t + 1) * kstep;
;             const char* a2 = last ? nA : cA + (size_t)(t + 2) * kstep; const char* b2 = last ? nB : cB + (size_t)(t + 2) * kstep;
;             const char* a3 = a2 + kstep; const char* b3 = b2 + kstep;
;             if (last && has_next) S.a_ready(nxt);
;             if constexpr (SP2) {
;             PG8_LDB(B0, 0, 0); PG8_LDB(B1, 0, 1); PG8_SCHED; PG8_LDA(At, 0, 0); PG8_STAGE(PG8_SA(1, 1), a1 + hstep, voffA);
;             PG8_WAIT_V(8); PG8_WAIT_L(0); PG8_BAR; PG8_MMA(0, 0, At, B0); PG8_MMA(0, 1, At, B1); PG8_BAR; PG8_SCHED;
;             PG8_LDA(At, 0, 1); PG8_STAGE(PG8_SB(0, 0), b2, voffB); PG8_STAGE(PG8_SB(0, 1), b2 + hstep, voffB); PG8_STAGE(PG8_SA(0, 0), a2, voffA);
;             PG8_WAIT_V(8); PG8_WAIT_L(0); PG8_BAR; PG8_MMA(1, 0, At, B0); PG8_MMA(1, 1, At, B1); PG8_BAR; PG8_SCHED;
;             PG8_LDB(B0, 1, 0); PG8_LDB(B1, 1, 1); PG8_SCHED; PG8_LDA(At, 1, 0); PG8_STAGE(PG8_SA(0, 1), a2 + hstep, voffA);
;             PG8_WAIT_V(8); PG8_WAIT_L(0); PG8_BAR; PG8_MMA(0, 0, At, B0); PG8_MMA(0, 1, At, B1); PG8_BAR; PG8_SCHED;
;             PG8_LDA(At, 1, 1); PG8_STAGE(PG8_SB(1, 0), b3, voffB); PG8_STAGE(PG8_SB(1, 1), b3 + hstep, voffB); PG8_STAGE(PG8_SA(1, 0), a3, voffA);
;             PG8_WAIT_V(8); PG8_WAIT_L(0); PG8_BAR; PG8_MMA(1, 0, At, B0); PG8_MMA(1, 1, At, B1); PG8_BAR; PG8_SCHED;
.LBB0_283:
	ds_read_b128 v[152:155], v149
	ds_read_b128 v[156:159], v149 offset:1024
	ds_read_b128 v[160:163], v149 offset:2048
	ds_read_b128 v[164:167], v149 offset:3072
	ds_read_b128 v[168:171], v150
	ds_read_b128 v[172:175], v150 offset:1024
	ds_read_b128 v[180:183], v150 offset:2048
	ds_read_b128 v[184:187], v150 offset:3072
	s_add_u32 s30, s66, 0xfff80080
	s_addc_u32 s31, s67, -1
	s_cmp_eq_u32 s85, 28
	s_cselect_b32 s71, s59, s31
	s_cselect_b32 s70, s81, s30
	s_cselect_b32 s69, s57, s84
	s_cselect_b32 s68, s82, s83
	s_add_i32 m0, s29, 0xc000
	ds_read_b128 v[188:191], v151
	ds_read_b128 v[192:195], v151 offset:1024
	ds_read_b128 v[196:199], v151 offset:2048
	ds_read_b128 v[200:203], v151 offset:3072
	ds_read_b128 v[204:207], v151 offset:4096
	ds_read_b128 v[208:211], v151 offset:5120
	ds_read_b128 v[212:215], v151 offset:6144
	ds_read_b128 v[216:219], v151 offset:7168
	global_load_lds_dwordx4 v136, s[66:67]
	s_add_i32 m0, s29, 0xe000
	s_nop 0
	global_load_lds_dwordx4 v138, s[66:67]
	s_waitcnt vmcnt(8)
	s_waitcnt lgkmcnt(0)
	s_barrier
	s_waitcnt lgkmcnt(0)
	v_mfma_f32_16x16x32_bf16 v[124:127], v[152:155], v[188:191], v[124:127]
	v_mfma_f32_16x16x32_bf16 v[120:123], v[160:163], v[188:191], v[120:123]
	v_mfma_f32_16x16x32_bf16 v[116:119], v[152:155], v[196:199], v[116:119]
	v_mfma_f32_16x16x32_bf16 v[108:111], v[160:163], v[196:199], v[108:111]
	v_mfma_f32_16x16x32_bf16 v[100:103], v[152:155], v[204:207], v[100:103]
	v_mfma_f32_16x16x32_bf16 v[92:95], v[160:163], v[204:207], v[92:95]
	v_mfma_f32_16x16x32_bf16 v[84:87], v[152:155], v[212:215], v[84:87]
	v_mfma_f32_16x16x32_bf16 v[76:79], v[160:163], v[212:215], v[76:79]
	v_mfma_f32_16x16x32_bf16 v[124:127], v[156:159], v[192:195], v[124:127]
	v_mfma_f32_16x16x32_bf16 v[120:123], v[164:167], v[192:195], v[120:123]
	v_mfma_f32_16x16x32_bf16 v[116:119], v[156:159], v[200:203], v[116:119]
	v_mfma_f32_16x16x32_bf16 v[108:111], v[164:167], v[200:203], v[108:111]
	v_mfma_f32_16x16x32_bf16 v[100:103], v[156:159], v[208:211], v[100:103]
	v_mfma_f32_16x16x32_bf16 v[92:95], v[164:167], v[208:211], v[92:95]
	v_mfma_f32_16x16x32_bf16 v[84:87], v[156:159], v[216:219], v[84:87]
	v_mfma_f32_16x16x32_bf16 v[76:79], v[164:167], v[216:219], v[76:79]
	v_mfma_f32_16x16x32_bf16 v[112:115], v[168:171], v[188:191], v[112:115]
	v_mfma_f32_16x16x32_bf16 v[104:107], v[180:183], v[188:191], v[104:107]
	v_mfma_f32_16x16x32_bf16 v[96:99], v[168:171], v[196:199], v[96:99]
	v_mfma_f32_16x16x32_bf16 v[88:91], v[180:183], v[196:199], v[88:91]
	v_mfma_f32_16x16x32_bf16 v[80:83], v[168:171], v[204:207], v[80:83]
	v_mfma_f32_16x16x32_bf16 v[72:75], v[180:183], v[204:207], v[72:75]
	v_mfma_f32_16x16x32_bf16 v[68:71], v[168:171], v[212:215], v[68:71]
	v_mfma_f32_16x16x32_bf16 v[64:67], v[180:183], v[212:215], v[64:67]
	v_mfma_f32_16x16x32_bf16 v[112:115], v[172:175], v[192:195], v[112:115]
	v_mfma_f32_16x16x32_bf16 v[104:107], v[184:187], v[192:195], v[104:107]
	v_mfma_f32_16x16x32_bf16 v[96:99], v[172:175], v[200:203], v[96:99]
	v_mfma_f32_16x16x32_bf16 v[88:91], v[184:187], v[200:203], v[88:91]
	v_mfma_f32_16x16x32_bf16 v[80:83], v[172:175], v[208:211], v[80:83]
	v_mfma_f32_16x16x32_bf16 v[72:75], v[184:187], v[208:211], v[72:75]
	v_mfma_f32_16x16x32_bf16 v[68:71], v[172:175], v[216:219], v[68:71]
	v_mfma_f32_16x16x32_bf16 v[64:67], v[184:187], v[216:219], v[64:67]
	s_barrier
	s_add_i32 s30, s74, s1
	s_mov_b32 m0, s30
	ds_read_b128 v[188:191], v151 offset:16384
	ds_read_b128 v[192:195], v151 offset:17408
	ds_read_b128 v[196:199], v151 offset:18432
	ds_read_b128 v[200:203], v151 offset:19456
	ds_read_b128 v[204:207], v151 offset:20480
	ds_read_b128 v[208:211], v151 offset:21504
	ds_read_b128 v[212:215], v151 offset:22528
	ds_read_b128 v[216:219], v151 offset:23552
	global_load_lds_dwordx4 v130, s[68:69]
	s_add_i32 m0, s30, 0x2000
	s_add_u32 s30, s68, 0x80000
	s_addc_u32 s31, s69, 0
	s_add_i32 s86, s75, s1
	global_load_lds_dwordx4 v134, s[68:69]
	s_mov_b32 m0, s86
	s_nop 0
	global_load_lds_dwordx4 v130, s[30:31]
	s_add_i32 m0, s86, 0x2000
	s_nop 0
	global_load_lds_dwordx4 v134, s[30:31]
	s_mov_b32 m0, s29
	s_nop 0
	global_load_lds_dwordx4 v128, s[70:71]
	s_mov_b32 m0, s33
	s_nop 0
	global_load_lds_dwordx4 v132, s[70:71]
	s_waitcnt vmcnt(8)
	s_waitcnt lgkmcnt(0)
	s_barrier
	s_waitcnt lgkmcnt(0)
	v_mfma_f32_16x16x32_bf16 v[60:63], v[152:155], v[188:191], v[60:63]
	v_mfma_f32_16x16x32_bf16 v[56:59], v[160:163], v[188:191], v[56:59]
	v_mfma_f32_16x16x32_bf16 v[52:55], v[152:155], v[196:199], v[52:55]
	v_mfma_f32_16x16x32_bf16 v[44:47], v[160:163], v[196:199], v[44:47]
	v_mfma_f32_16x16x32_bf16 v[36:39], v[152:155], v[204:207], v[36:39]
	v_mfma_f32_16x16x32_bf16 v[28:31], v[160:163], v[204:207], v[28:31]
	v_mfma_f32_16x16x32_bf16 v[20:23], v[152:155], v[212:215], v[20:23]
	v_mfma_f32_16x16x32_bf16 v[12:15], v[160:163], v[212:215], v[12:15]
	v_mfma_f32_16x16x32_bf16 v[60:63], v[156:159], v[192:195], v[60:63]
	v_mfma_f32_16x16x32_bf16 v[56:59], v[164:167], v[192:195], v[56:59]
	v_mfma_f32_16x16x32_bf16 v[52:55], v[156:159], v[200:203], v[52:55]
	v_mfma_f32_16x16x32_bf16 v[44:47], v[164:167], v[200:203], v[44:47]
	v_mfma_f32_16x16x32_bf16 v[36:39], v[156:159], v[208:211], v[36:39]
	v_mfma_f32_16x16x32_bf16 v[28:31], v[164:167], v[208:211], v[28:31]
	v_mfma_f32_16x16x32_bf16 v[20:23], v[156:159], v[216:219], v[20:23]
	v_mfma_f32_16x16x32_bf16 v[12:15], v[164:167], v[216:219], v[12:15]
	v_mfma_f32_16x16x32_bf16 v[48:51], v[168:171], v[188:191], v[48:51]
	v_mfma_f32_16x16x32_bf16 v[40:43], v[180:183], v[188:191], v[40:43]
	v_mfma_f32_16x16x32_bf16 v[32:35], v[168:171], v[196:199], v[32:35]
	v_mfma_f32_16x16x32_bf16 v[24:27], v[180:183], v[196:199], v[24:27]
	v_mfma_f32_16x16x32_bf16 v[16:19], v[168:171], v[204:207], v[16:19]
	v_mfma_f32_16x16x32_bf16 v[8:11], v[180:183], v[204:207], v[8:11]
	v_mfma_f32_16x16x32_bf16 v[4:7], v[168:171], v[212:215], v[4:7]
	v_mfma_f32_16x16x32_bf16 v[0:3], v[180:183], v[212:215], v[0:3]
	v_mfma_f32_16x16x32_bf16 v[48:51], v[172:175], v[192:195], v[48:51]
	v_mfma_f32_16x16x32_bf16 v[40:43], v[184:187], v[192:195], v[40:43]
	v_mfma_f32_16x16x32_bf16 v[32:35], v[172:175], v[200:203], v[32:35]
	v_mfma_f32_16x16x32_bf16 v[24:27], v[184:187], v[200:203], v[24:27]
	v_mfma_f32_16x16x32_bf16 v[16:19], v[172:175], v[208:211], v[16:19]
	v_mfma_f32_16x16x32_bf16 v[8:11], v[184:187], v[208:211], v[8:11]
	v_mfma_f32_16x16x32_bf16 v[4:7], v[172:175], v[216:219], v[4:7]
	v_mfma_f32_16x16x32_bf16 v[0:3], v[184:187], v[216:219], v[0:3]
	s_barrier
; #define PG8_STAGE(bufoff, gbase, voff) do { _Pragma("unroll") for (int _i = 0; _i < 2; ++_i) \
;         __builtin_amdgcn_global_load_lds((const unsigned*)((const char*)(gbase) + (voff)[_i]), (PG8_LAS unsigned*)(lds + (bufoff) + ldsw + _i * 8192), 16, 0, 0); } while (0)
; #define PG8_LDA(dst, b, h) do { _Pragma("unroll") for (int m = 0; m < 4; ++m) _Pragma("unroll") for (int k = 0; k < 2; ++k) dst[m][k] = *(const PG8_LAS bf16x8*)(lds + PG8_SA(b, h) + aoff + m * 2048 + k * 1024); } while (0)
; #define PG8_LDB(dst, b, h) do { _Pragma("unroll") for (int n = 0; n < 2; ++n) _Pragma("unroll") for (int k = 0; k < 2; ++k) dst[n][k] = *(const PG8_LAS bf16x8*)(lds + PG8_SB(b, h) + boff + n * 2048 + k * 1024); } while (0)
; template <class Epi, class Sched, bool ALIGN_EPI = false, bool SP2 = false>
; __device__ __forceinline__ void gemm_phase(PG8_LAS unsigned char* lds, const Gemm g, const Sched& S, const Epi& E) {
;     ...
;         for (int t = 0; t < nt; t += 2) {
;             const bool last = (t == nt - 2);
;             const char* a1 = cA + (size_t)(t + 1) * kstep;
;             const char* a2 = last ? nA : cA + (size_t)(t + 2) * kstep; const char* b2 = last ? nB : cB + (size_t)(t + 2) * kstep;
;             const char* a3 = a2 + kstep; const char* b3 = b2 + kstep;
;             if (last && has_next) S.a_ready(nxt);
;             if constexpr (SP2) {
;             PG8_LDB(B0, 0, 0); PG8_LDB(B1, 0, 1); PG8_SCHED; PG8_LDA(At, 0, 0); PG8_STAGE(PG8_SA(1, 1), a1 + hstep, voffA);
;             PG8_WAIT_V(8); PG8_WAIT_L(0); PG8_BAR; PG8_MMA(0, 0, At, B0); PG8_MMA(0, 1, At, B1); PG8_BAR; PG8_SCHED;
;             PG8_LDA(At, 0, 1); PG8_STAGE(PG8_SB(0, 0), b2, voffB); PG8_STAGE(PG8_SB(0, 1), b2 + hstep, voffB); PG8_STAGE(PG8_SA(0, 0), a2, voffA);
;             PG8_WAIT_V(8); PG8_WAIT_L(0); PG8_BAR; PG8_MMA(1, 0, At, B0); PG8_MMA(1, 1, At, B1); PG8_BAR; PG8_SCHED;
;             PG8_LDB(B0, 1, 0); PG8_LDB(B1, 1, 1); PG8_SCHED; PG8_LDA(At, 1, 0); PG8_STAGE(PG8_SA(0, 1), a2 + hstep, voffA);
;             PG8_WAIT_V(8); PG8_WAIT_L(0); PG8_BAR; PG8_MMA(0, 0, At, B0); PG8_MMA(0, 1, At, B1); PG8_BAR; PG8_SCHED;
;             PG8_LDA(At, 1, 1); PG8_STAGE(PG8_SB(1, 0), b3, voffB); PG8_STAGE(PG8_SB(1, 1), b3 + hstep, voffB); PG8_STAGE(PG8_SA(1, 0), a3, voffA);
;             PG8_WAIT_V(8); PG8_WAIT_L(0); PG8_BAR; PG8_MMA(1, 0, At, B0); PG8_MMA(1, 1, At, B1); PG8_BAR; PG8_SCHED;
	s_add_i32 s86, 0, 0x18000
	s_add_i32 s87, 0, 0x1c000
	v_add_u32_e32 v164, s86, v147
	v_add_u32_e32 v179, s87, v147
	ds_read_b128 v[152:155], v164
	ds_read_b128 v[156:159], v164 offset:1024
	ds_read_b128 v[160:163], v164 offset:2048
	ds_read_b128 v[164:167], v164 offset:3072
	ds_read_b128 v[168:171], v179
	ds_read_b128 v[172:175], v179 offset:1024
	ds_read_b128 v[180:183], v179 offset:2048
	ds_read_b128 v[184:187], v179 offset:3072
	s_add_u32 s30, s70, 0x80000
	s_addc_u32 s31, s71, 0
	s_mov_b32 m0, s46
	ds_read_b128 v[188:191], v151 offset:32768
	ds_read_b128 v[192:195], v151 offset:33792
	ds_read_b128 v[196:199], v151 offset:34816
	ds_read_b128 v[200:203], v151 offset:35840
	ds_read_b128 v[204:207], v151 offset:36864
	ds_read_b128 v[208:211], v151 offset:37888
	ds_read_b128 v[212:215], v151 offset:38912
	ds_read_b128 v[216:219], v151 offset:39936
	global_load_lds_dwordx4 v128, s[30:31]
	s_mov_b32 m0, s47
	s_nop 0
	global_load_lds_dwordx4 v132, s[30:31]
	s_waitcnt vmcnt(8)
	s_waitcnt lgkmcnt(0)
	s_barrier
	s_waitcnt lgkmcnt(0)
	v_mfma_f32_16x16x32_bf16 v[124:127], v[152:155], v[188:191], v[124:127]
	v_mfma_f32_16x16x32_bf16 v[120:123], v[160:163], v[188:191], v[120:123]
	v_mfma_f32_16x16x32_bf16 v[116:119], v[152:155], v[196:199], v[116:119]
	v_mfma_f32_16x16x32_bf16 v[108:111], v[160:163], v[196:199], v[108:111]
	v_mfma_f32_16x16x32_bf16 v[100:103], v[152:155], v[204:207], v[100:103]
	v_mfma_f32_16x16x32_bf16 v[92:95], v[160:163], v[204:207], v[92:95]
	v_mfma_f32_16x16x32_bf16 v[84:87], v[152:155], v[212:215], v[84:87]
	v_mfma_f32_16x16x32_bf16 v[76:79], v[160:163], v[212:215], v[76:79]
	v_mfma_f32_16x16x32_bf16 v[124:127], v[156:159], v[192:195], v[124:127]
	v_mfma_f32_16x16x32_bf16 v[120:123], v[164:167], v[192:195], v[120:123]
	v_mfma_f32_16x16x32_bf16 v[116:119], v[156:159], v[200:203], v[116:119]
	v_mfma_f32_16x16x32_bf16 v[108:111], v[164:167], v[200:203], v[108:111]
	v_mfma_f32_16x16x32_bf16 v[100:103], v[156:159], v[208:211], v[100:103]
	v_mfma_f32_16x16x32_bf16 v[92:95], v[164:167], v[208:211], v[92:95]
	v_mfma_f32_16x16x32_bf16 v[84:87], v[156:159], v[216:219], v[84:87]
	v_mfma_f32_16x16x32_bf16 v[76:79], v[164:167], v[216:219], v[76:79]
	v_mfma_f32_16x16x32_bf16 v[112:115], v[168:171], v[188:191], v[112:115]
	v_mfma_f32_16x16x32_bf16 v[104:107], v[180:183], v[188:191], v[104:107]
	v_mfma_f32_16x16x32_bf16 v[96:99], v[168:171], v[196:199], v[96:99]
	v_mfma_f32_16x16x32_bf16 v[88:91], v[180:183], v[196:199], v[88:91]
	v_mfma_f32_16x16x32_bf16 v[80:83], v[168:171], v[204:207], v[80:83]
	v_mfma_f32_16x16x32_bf16 v[72:75], v[180:183], v[204:207], v[72:75]
	v_mfma_f32_16x16x32_bf16 v[68:71], v[168:171], v[212:215], v[68:71]
	v_mfma_f32_16x16x32_bf16 v[64:67], v[180:183], v[212:215], v[64:67]
	v_mfma_f32_16x16x32_bf16 v[112:115], v[172:175], v[192:195], v[112:115]
	v_mfma_f32_16x16x32_bf16 v[104:107], v[184:187], v[192:195], v[104:107]
	v_mfma_f32_16x16x32_bf16 v[96:99], v[172:175], v[200:203], v[96:99]
	v_mfma_f32_16x16x32_bf16 v[88:91], v[184:187], v[200:203], v[88:91]
	v_mfma_f32_16x16x32_bf16 v[80:83], v[172:175], v[208:211], v[80:83]
	v_mfma_f32_16x16x32_bf16 v[72:75], v[184:187], v[208:211], v[72:75]
	v_mfma_f32_16x16x32_bf16 v[68:71], v[172:175], v[216:219], v[68:71]
	v_mfma_f32_16x16x32_bf16 v[64:67], v[184:187], v[216:219], v[64:67]
	s_barrier
	s_add_i32 s30, s86, s1
	s_mov_b32 m0, s30
	ds_read_b128 v[188:191], v151 offset:49152
	ds_read_b128 v[192:195], v151 offset:50176
	ds_read_b128 v[196:199], v151 offset:51200
	ds_read_b128 v[200:203], v151 offset:52224
	ds_read_b128 v[204:207], v151 offset:53248
	ds_read_b128 v[208:211], v151 offset:54272
	ds_read_b128 v[212:215], v151 offset:55296
	ds_read_b128 v[216:219], v151 offset:56320
	s_add_u32 s8, s68, 0x80
	s_addc_u32 s9, s69, 0
	global_load_lds_dwordx4 v130, s[8:9]
	s_add_i32 m0, s30, 0x2000
	s_add_u32 s30, s68, 0x80080
	s_addc_u32 s31, s69, 0
	s_add_i32 s68, s87, s1
	global_load_lds_dwordx4 v134, s[8:9]
	s_mov_b32 m0, s68
	s_nop 0
	global_load_lds_dwordx4 v130, s[30:31]
	s_add_i32 m0, s68, 0x2000
	s_nop 0
	global_load_lds_dwordx4 v134, s[30:31]
	s_mov_b32 m0, s72
	s_nop 0
	s_add_u32 s8, s70, 0x80
	s_addc_u32 s9, s71, 0
	global_load_lds_dwordx4 v128, s[8:9]
	s_mov_b32 m0, s73
	s_nop 0
	global_load_lds_dwordx4 v132, s[8:9]
	s_waitcnt vmcnt(8)
	s_waitcnt lgkmcnt(0)
	s_barrier
	s_waitcnt lgkmcnt(0)
	v_mfma_f32_16x16x32_bf16 v[60:63], v[152:155], v[188:191], v[60:63]
	v_mfma_f32_16x16x32_bf16 v[56:59], v[160:163], v[188:191], v[56:59]
	v_mfma_f32_16x16x32_bf16 v[52:55], v[152:155], v[196:199], v[52:55]
	v_mfma_f32_16x16x32_bf16 v[44:47], v[160:163], v[196:199], v[44:47]
	v_mfma_f32_16x16x32_bf16 v[36:39], v[152:155], v[204:207], v[36:39]
	v_mfma_f32_16x16x32_bf16 v[28:31], v[160:163], v[204:207], v[28:31]
	v_mfma_f32_16x16x32_bf16 v[20:23], v[152:155], v[212:215], v[20:23]
	v_mfma_f32_16x16x32_bf16 v[12:15], v[160:163], v[212:215], v[12:15]
	v_mfma_f32_16x16x32_bf16 v[60:63], v[156:159], v[192:195], v[60:63]
	v_mfma_f32_16x16x32_bf16 v[56:59], v[164:167], v[192:195], v[56:59]
	v_mfma_f32_16x16x32_bf16 v[52:55], v[156:159], v[200:203], v[52:55]
	v_mfma_f32_16x16x32_bf16 v[44:47], v[164:167], v[200:203], v[44:47]
	v_mfma_f32_16x16x32_bf16 v[36:39], v[156:159], v[208:211], v[36:39]
	v_mfma_f32_16x16x32_bf16 v[28:31], v[164:167], v[208:211], v[28:31]
	v_mfma_f32_16x16x32_bf16 v[20:23], v[156:159], v[216:219], v[20:23]
	v_mfma_f32_16x16x32_bf16 v[12:15], v[164:167], v[216:219], v[12:15]
	v_mfma_f32_16x16x32_bf16 v[48:51], v[168:171], v[188:191], v[48:51]
	v_mfma_f32_16x16x32_bf16 v[40:43], v[180:183], v[188:191], v[40:43]
	v_mfma_f32_16x16x32_bf16 v[32:35], v[168:171], v[196:199], v[32:35]
	v_mfma_f32_16x16x32_bf16 v[24:27], v[180:183], v[196:199], v[24:27]
	v_mfma_f32_16x16x32_bf16 v[16:19], v[168:171], v[204:207], v[16:19]
	v_mfma_f32_16x16x32_bf16 v[8:11], v[180:183], v[204:207], v[8:11]
	v_mfma_f32_16x16x32_bf16 v[4:7], v[168:171], v[212:215], v[4:7]
	v_mfma_f32_16x16x32_bf16 v[0:3], v[180:183], v[212:215], v[0:3]
	v_mfma_f32_16x16x32_bf16 v[48:51], v[172:175], v[192:195], v[48:51]
	v_mfma_f32_16x16x32_bf16 v[40:43], v[184:187], v[192:195], v[40:43]
	v_mfma_f32_16x16x32_bf16 v[32:35], v[172:175], v[200:203], v[32:35]
	v_mfma_f32_16x16x32_bf16 v[24:27], v[184:187], v[200:203], v[24:27]
	v_mfma_f32_16x16x32_bf16 v[16:19], v[172:175], v[208:211], v[16:19]
	v_mfma_f32_16x16x32_bf16 v[8:11], v[184:187], v[208:211], v[8:11]
	v_mfma_f32_16x16x32_bf16 v[4:7], v[172:175], v[216:219], v[4:7]
	v_mfma_f32_16x16x32_bf16 v[0:3], v[184:187], v[216:219], v[0:3]
	s_add_i32 s85, s85, 2
	s_add_u32 s66, s66, 0x100
	s_addc_u32 s67, s67, 0
	s_add_u32 s83, s83, 0x100
	s_addc_u32 s84, s84, 0
	s_cmp_gt_u32 s85, 29
	s_barrier
; __device__ __forceinline__ unsigned cvt_pk_bf16(float lo, float hi) { unsigned r; asm volatile("v_cvt_pk_bf16_f32 %0, %1, %2" : "=v"(r) : "v"(lo), "v"(hi)); return r; }
; #define PG8_WAIT_V(n) asm volatile("s_waitcnt vmcnt(" #n ")" ::: "memory")
; #define PG8_BAR __builtin_amdgcn_s_barrier()
;     __device__ __forceinline__ void operator()(const f32x4 (&acc)[2][2][4][2], const Unit& u, int wr, int wc, int fr, int fq) const {
;         const int row0 = u.pm * BM + wr * 64 + fr; const int col0 = u.pn * BM + wc * 32 + 8 * fq;
; #pragma unroll
;         for (int ai = 0; ai < 2; ++ai)
; #pragma unroll
;             for (int m = 0; m < 4; ++m) { bf16_t* rowp = O + (size_t)(row0 + ai * HALF + m * 16) * ldc + col0;
; #pragma unroll
;                 for (int bj = 0; bj < 2; ++bj) { const f32x4 v0 = acc[ai][bj][m][0], v1 = acc[ai][bj][m][1];
;                     u32x4 w; w.x = cvt_pk_bf16(v0[0], v0[1]); w.y = cvt_pk_bf16(v0[2], v0[3]); w.z = cvt_pk_bf16(v1[0], v1[1]); w.w = cvt_pk_bf16(v1[2], v1[3]);
;                     *(u32x4*)(rowp + bj * HALF) = w; } }
;     }
; template <class Epi, class Sched, bool ALIGN_EPI = false, bool SP2 = false>
; __device__ __forceinline__ void gemm_phase(PG8_LAS unsigned char* lds, const Gemm g, const Sched& S, const Epi& E) {
;     ...
;         }
;         if constexpr (ALIGN_EPI) { if (wr == 0) PG8_BAR; }
;         if constexpr (!Epi::AFTER_DRAIN) { E(acc, cur, wr, wc, fr, fq); S.done(cur); }
;         if (!has_next) break;
; #pragma unroll
;         for (int a = 0; a < 2; ++a)
; #pragma unroll
;             for (int b = 0; b < 2; ++b)
; #pragma unroll
;                 for (int m = 0; m < 4; ++m)
; #pragma unroll
;                     for (int n = 0; n < 2; ++n) acc[a][b][m][n] = (f32x4){0.f, 0.f, 0.f, 0.f};
;         cur = nxt; cA = nA; cB = nB; ++ui;
;         if constexpr (ALIGN_EPI) { if (wr == 1) PG8_BAR; }
;     }
;     PG8_WAIT_V(0);
;     if constexpr (!ALIGN_EPI) { if (wr == 0) PG8_BAR; }
	s_cbranch_scc0 .LBB0_283
	v_lshl_add_u32 v152, s64, 8, v146
	v_lshl_or_b32 v144, s80, 8, v148
	v_ashrrev_i32_e32 v153, 31, v152
	v_ashrrev_i32_e32 v145, 31, v144
	v_lshlrev_b64 v[154:155], 12, v[152:153]
	v_lshl_add_u64 v[154:155], s[18:19], 0, v[154:155]
	v_lshlrev_b64 v[156:157], 1, v[144:145]
	v_lshl_add_u64 v[144:145], v[154:155], 0, v[156:157]
	v_cvt_pk_bf16_f32 v124, v124, v125
	v_cvt_pk_bf16_f32 v125, v126, v127
	v_cvt_pk_bf16_f32 v126, v120, v121
	v_cvt_pk_bf16_f32 v127, v122, v123
	global_store_dwordx4 v[144:145], v[124:127], off
	v_cvt_pk_bf16_f32 v112, v112, v113
	v_cvt_pk_bf16_f32 v113, v114, v115
	v_cvt_pk_bf16_f32 v114, v104, v105
	v_or_b32_e32 v104, 16, v152
	v_ashrrev_i32_e32 v105, 31, v104
	v_lshlrev_b64 v[104:105], 12, v[104:105]
	v_lshl_add_u64 v[104:105], s[18:19], 0, v[104:105]
	v_cvt_pk_bf16_f32 v115, v106, v107
	global_store_dwordx4 v[144:145], v[112:115], off offset:256
	s_mov_b32 s80, s56
	s_mov_b32 s64, s58
	v_lshl_add_u64 v[112:113], v[104:105], 0, v[156:157]
	v_cvt_pk_bf16_f32 v104, v116, v117
	v_cvt_pk_bf16_f32 v105, v118, v119
	v_cvt_pk_bf16_f32 v106, v108, v109
	v_cvt_pk_bf16_f32 v107, v110, v111
	global_store_dwordx4 v[112:113], v[104:107], off
	v_cvt_pk_bf16_f32 v96, v96, v97
	v_cvt_pk_bf16_f32 v97, v98, v99
	v_cvt_pk_bf16_f32 v98, v88, v89
	v_or_b32_e32 v88, 32, v152
	v_ashrrev_i32_e32 v89, 31, v88
	v_lshlrev_b64 v[88:89], 12, v[88:89]
	v_lshl_add_u64 v[88:89], s[18:19], 0, v[88:89]
	v_cvt_pk_bf16_f32 v99, v90, v91
	global_store_dwordx4 v[112:113], v[96:99], off offset:256
	s_mov_b64 s[68:69], s[62:63]
	s_mov_b64 s[66:67], s[60:61]
	v_lshl_add_u64 v[96:97], v[88:89], 0, v[156:157]
	v_cvt_pk_bf16_f32 v88, v100, v101
	v_cvt_pk_bf16_f32 v89, v102, v103
	v_cvt_pk_bf16_f32 v90, v92, v93
	v_cvt_pk_bf16_f32 v91, v94, v95
	global_store_dwordx4 v[96:97], v[88:91], off
	v_cvt_pk_bf16_f32 v80, v80, v81
	v_cvt_pk_bf16_f32 v81, v82, v83
	v_cvt_pk_bf16_f32 v82, v72, v73
	v_or_b32_e32 v72, 48, v152
	v_ashrrev_i32_e32 v73, 31, v72
	v_lshlrev_b64 v[72:73], 12, v[72:73]
	v_lshl_add_u64 v[72:73], s[18:19], 0, v[72:73]
	v_cvt_pk_bf16_f32 v83, v74, v75
	global_store_dwordx4 v[96:97], v[80:83], off offset:256
	s_nop 1
	v_lshl_add_u64 v[80:81], v[72:73], 0, v[156:157]
	v_cvt_pk_bf16_f32 v72, v84, v85
	v_cvt_pk_bf16_f32 v73, v86, v87
	v_cvt_pk_bf16_f32 v74, v76, v77
	v_cvt_pk_bf16_f32 v75, v78, v79
	global_store_dwordx4 v[80:81], v[72:75], off
	v_cvt_pk_bf16_f32 v68, v68, v69
	v_cvt_pk_bf16_f32 v69, v70, v71
	v_cvt_pk_bf16_f32 v70, v64, v65
	v_cvt_pk_bf16_f32 v71, v66, v67
	global_store_dwordx4 v[80:81], v[68:71], off offset:256
	v_cvt_pk_bf16_f32 v60, v60, v61
	v_cvt_pk_bf16_f32 v61, v62, v63
	v_cvt_pk_bf16_f32 v62, v56, v57
	v_add_co_u32_e32 v56, vcc, s76, v144
	v_lshl_add_u64 v[64:65], v[144:145], 0, s[6:7]
	s_nop 0
	v_addc_co_u32_e32 v57, vcc, 0, v145, vcc
	v_cvt_pk_bf16_f32 v63, v58, v59
	global_store_dwordx4 v[56:57], v[60:63], off
	v_cvt_pk_bf16_f32 v48, v48, v49
	v_cvt_pk_bf16_f32 v49, v50, v51
	v_cvt_pk_bf16_f32 v50, v40, v41
	v_cvt_pk_bf16_f32 v51, v42, v43
	global_store_dwordx4 v[64:65], v[48:51], off offset:256
	v_cvt_pk_bf16_f32 v40, v52, v53
	v_cvt_pk_bf16_f32 v41, v54, v55
	v_cvt_pk_bf16_f32 v42, v44, v45
	v_add_co_u32_e32 v44, vcc, s77, v144
	s_nop 0
	v_lshl_add_u64 v[48:49], v[144:145], 0, s[10:11]
	v_addc_co_u32_e32 v45, vcc, 0, v145, vcc
	v_cvt_pk_bf16_f32 v43, v46, v47
	global_store_dwordx4 v[44:45], v[40:43], off
	v_cvt_pk_bf16_f32 v32, v32, v33
	v_cvt_pk_bf16_f32 v33, v34, v35
	v_cvt_pk_bf16_f32 v34, v24, v25
	v_cvt_pk_bf16_f32 v35, v26, v27
	global_store_dwordx4 v[48:49], v[32:35], off offset:256
	v_cvt_pk_bf16_f32 v24, v36, v37
	v_cvt_pk_bf16_f32 v25, v38, v39
	v_cvt_pk_bf16_f32 v26, v28, v29
	v_add_co_u32_e32 v28, vcc, s78, v144
	s_nop 0
	v_lshl_add_u64 v[32:33], v[144:145], 0, s[36:37]
	v_addc_co_u32_e32 v29, vcc, 0, v145, vcc
	v_cvt_pk_bf16_f32 v27, v30, v31
	global_store_dwordx4 v[28:29], v[24:27], off
	v_cvt_pk_bf16_f32 v16, v16, v17
	v_cvt_pk_bf16_f32 v17, v18, v19
	v_cvt_pk_bf16_f32 v18, v8, v9
	v_cvt_pk_bf16_f32 v19, v10, v11
	global_store_dwordx4 v[32:33], v[16:19], off offset:256
	v_cvt_pk_bf16_f32 v8, v20, v21
	v_cvt_pk_bf16_f32 v9, v22, v23
	v_cvt_pk_bf16_f32 v10, v12, v13
	v_add_co_u32_e32 v12, vcc, s79, v144
	s_nop 0
	v_lshl_add_u64 v[16:17], v[144:145], 0, s[54:55]
	v_addc_co_u32_e32 v13, vcc, 0, v145, vcc
	s_and_b64 vcc, exec, s[4:5]
	v_cvt_pk_bf16_f32 v11, v14, v15
	global_store_dwordx4 v[12:13], v[8:11], off
	v_cvt_pk_bf16_f32 v4, v4, v5
	v_cvt_pk_bf16_f32 v5, v6, v7
	v_cvt_pk_bf16_f32 v6, v0, v1
	v_cvt_pk_bf16_f32 v7, v2, v3
	global_store_dwordx4 v[16:17], v[4:7], off offset:256
	s_cbranch_vccz .LBB0_276
	s_waitcnt vmcnt(0)
	s_cmpk_gt_u32 s0, 0xff
	s_cbranch_scc1 .LBB0_287
	s_barrier

; #define PG8_STAGE(bufoff, gbase, voff) do { _Pragma("unroll") for (int _i = 0; _i < 2; ++_i) \
;         __builtin_amdgcn_global_load_lds((const unsigned*)((const char*)(gbase) + (voff)[_i]), (PG8_LAS unsigned*)(lds + (bufoff) + ldsw + _i * 8192), 16, 0, 0); } while (0)
; #define PG8_LDA(dst, b, h) do { _Pragma("unroll") for (int m = 0; m < 4; ++m) _Pragma("unroll") for (int k = 0; k < 2; ++k) dst[m][k] = *(const PG8_LAS bf16x8*)(lds + PG8_SA(b, h) + aoff + m * 2048 + k * 1024); } while (0)
; #define PG8_LDB(dst, b, h) do { _Pragma("unroll") for (int n = 0; n < 2; ++n) _Pragma("unroll") for (int k = 0; k < 2; ++k) dst[n][k] = *(const PG8_LAS bf16x8*)(lds + PG8_SB(b, h) + boff + n * 2048 + k * 1024); } while (0)
; template <class Epi, class Sched, bool ALIGN_EPI = false, bool SP2 = false>
; __device__ __forceinline__ void gemm_phase(PG8_LAS unsigned char* lds, const Gemm g, const Sched& S, const Epi& E) {
;     ...
;         for (int t = 0; t < nt; t += 2) {
;             const bool last = (t == nt - 2);
;             const char* a1 = cA + (size_t)(t + 1) * kstep;
;             const char* a2 = last ? nA : cA + (size_t)(t + 2) * kstep; const char* b2 = last ? nB : cB + (size_t)(t + 2) * kstep;
;             const char* a3 = a2 + kstep; const char* b3 = b2 + kstep;
;             if (last && has_next) S.a_ready(nxt);
;             if constexpr (SP2) {
;             PG8_LDB(B0, 0, 0); PG8_LDB(B1, 0, 1); PG8_SCHED; PG8_LDA(At, 0, 0); PG8_STAGE(PG8_SA(1, 1), a1 + hstep, voffA);
;             PG8_WAIT_V(8); PG8_WAIT_L(0); PG8_BAR; PG8_MMA(0, 0, At, B0); PG8_MMA(0, 1, At, B1); PG8_BAR; PG8_SCHED;
;             PG8_LDA(At, 0, 1); PG8_STAGE(PG8_SB(0, 0), b2, voffB); PG8_STAGE(PG8_SB(0, 1), b2 + hstep, voffB); PG8_STAGE(PG8_SA(0, 0), a2, voffA);
;             PG8_WAIT_V(8); PG8_WAIT_L(0); PG8_BAR; PG8_MMA(1, 0, At, B0); PG8_MMA(1, 1, At, B1); PG8_BAR; PG8_SCHED;
;             PG8_LDB(B0, 1, 0); PG8_LDB(B1, 1, 1); PG8_SCHED; PG8_LDA(At, 1, 0); PG8_STAGE(PG8_SA(0, 1), a2 + hstep, voffA);
;             PG8_WAIT_V(8); PG8_WAIT_L(0); PG8_BAR; PG8_MMA(0, 0, At, B0); PG8_MMA(0, 1, At, B1); PG8_BAR; PG8_SCHED;
;             PG8_LDA(At, 1, 1); PG8_STAGE(PG8_SB(1, 0), b3, voffB); PG8_STAGE(PG8_SB(1, 1), b3 + hstep, voffB); PG8_STAGE(PG8_SA(1, 0), a3, voffA);
;             PG8_WAIT_V(8); PG8_WAIT_L(0); PG8_BAR; PG8_MMA(1, 0, At, B0); PG8_MMA(1, 1, At, B1); PG8_BAR; PG8_SCHED;
.LBB0_404:
	ds_read_b128 v[118:121], v217
	ds_read_b128 v[126:129], v217 offset:1024
	ds_read_b128 v[130:133], v217 offset:2048
	ds_read_b128 v[134:137], v217 offset:3072
	ds_read_b128 v[138:141], v218
	ds_read_b128 v[142:145], v218 offset:1024
	ds_read_b128 v[146:149], v218 offset:2048
	ds_read_b128 v[150:153], v218 offset:3072
	s_add_u32 s30, s10, 0xfff80080
	s_addc_u32 s31, s11, -1
	s_cmp_eq_u32 s65, 28
	s_cselect_b32 s75, s1, s31
	s_cselect_b32 s74, s22, s30
	s_cselect_b32 s73, s33, s63
	s_cselect_b32 s72, s46, s47
	s_add_i32 m0, s77, 0xc000
	ds_read_b128 v[154:157], v219
	ds_read_b128 v[166:169], v219 offset:1024
	ds_read_b128 v[170:173], v219 offset:2048
	ds_read_b128 v[174:177], v219 offset:3072
	ds_read_b128 v[204:207], v219 offset:4096
	ds_read_b128 v[208:211], v219 offset:5120
	ds_read_b128 v[226:229], v219 offset:6144
	ds_read_b128 v[230:233], v219 offset:7168
	global_load_lds_dwordx4 v196, s[10:11]
	s_add_i32 m0, s77, 0xe000
	s_nop 0
	global_load_lds_dwordx4 v198, s[10:11]
	s_waitcnt vmcnt(8)
	s_waitcnt lgkmcnt(0)
	s_barrier
	s_waitcnt lgkmcnt(0)
	v_mfma_f32_16x16x32_bf16 v[162:165], v[118:121], v[154:157], v[162:165]
	v_mfma_f32_16x16x32_bf16 v[60:63], v[130:133], v[154:157], v[60:63]
	v_mfma_f32_16x16x32_bf16 v[122:125], v[118:121], v[170:173], v[122:125]
	v_mfma_f32_16x16x32_bf16 v[52:55], v[130:133], v[170:173], v[52:55]
	v_mfma_f32_16x16x32_bf16 v[108:111], v[118:121], v[204:207], v[108:111]
	v_mfma_f32_16x16x32_bf16 v[44:47], v[130:133], v[204:207], v[44:47]
	v_mfma_f32_16x16x32_bf16 v[104:107], v[118:121], v[226:229], v[104:107]
	v_mfma_f32_16x16x32_bf16 v[40:43], v[130:133], v[226:229], v[40:43]
	v_mfma_f32_16x16x32_bf16 v[162:165], v[126:129], v[166:169], v[162:165]
	v_mfma_f32_16x16x32_bf16 v[60:63], v[134:137], v[166:169], v[60:63]
	v_mfma_f32_16x16x32_bf16 v[122:125], v[126:129], v[174:177], v[122:125]
	v_mfma_f32_16x16x32_bf16 v[52:55], v[134:137], v[174:177], v[52:55]
	v_mfma_f32_16x16x32_bf16 v[108:111], v[126:129], v[208:211], v[108:111]
	v_mfma_f32_16x16x32_bf16 v[44:47], v[134:137], v[208:211], v[44:47]
	v_mfma_f32_16x16x32_bf16 v[104:107], v[126:129], v[230:233], v[104:107]
	v_mfma_f32_16x16x32_bf16 v[40:43], v[134:137], v[230:233], v[40:43]
	v_mfma_f32_16x16x32_bf16 v[158:161], v[138:141], v[154:157], v[158:161]
	v_mfma_f32_16x16x32_bf16 v[56:59], v[146:149], v[154:157], v[56:59]
	v_mfma_f32_16x16x32_bf16 v[112:115], v[138:141], v[170:173], v[114:117]
	v_mfma_f32_16x16x32_bf16 v[48:51], v[146:149], v[170:173], v[48:51]
	v_mfma_f32_16x16x32_bf16 v[100:103], v[138:141], v[204:207], v[100:103]
	v_mfma_f32_16x16x32_bf16 v[36:39], v[146:149], v[204:207], v[36:39]
	v_mfma_f32_16x16x32_bf16 v[96:99], v[138:141], v[226:229], v[96:99]
	v_mfma_f32_16x16x32_bf16 v[32:35], v[146:149], v[226:229], v[32:35]
	v_mfma_f32_16x16x32_bf16 v[158:161], v[142:145], v[166:169], v[158:161]
	v_mfma_f32_16x16x32_bf16 v[56:59], v[150:153], v[166:169], v[56:59]
	v_mfma_f32_16x16x32_bf16 v[112:115], v[142:145], v[174:177], v[112:115]
	v_mfma_f32_16x16x32_bf16 v[48:51], v[150:153], v[174:177], v[48:51]
	v_mfma_f32_16x16x32_bf16 v[100:103], v[142:145], v[208:211], v[100:103]
	v_mfma_f32_16x16x32_bf16 v[36:39], v[150:153], v[208:211], v[36:39]
	v_mfma_f32_16x16x32_bf16 v[96:99], v[142:145], v[230:233], v[96:99]
	v_mfma_f32_16x16x32_bf16 v[32:35], v[150:153], v[230:233], v[32:35]
	s_barrier
	s_add_i32 s30, s85, s29
	s_mov_b32 m0, s30
	ds_read_b128 v[154:157], v219 offset:16384
	ds_read_b128 v[166:169], v219 offset:17408
	ds_read_b128 v[170:173], v219 offset:18432
	ds_read_b128 v[174:177], v219 offset:19456
	ds_read_b128 v[204:207], v219 offset:20480
	ds_read_b128 v[208:211], v219 offset:21504
	ds_read_b128 v[226:229], v219 offset:22528
	ds_read_b128 v[230:233], v219 offset:23552
	global_load_lds_dwordx4 v184, s[72:73]
	s_add_i32 m0, s30, 0x2000
	s_add_u32 s30, s72, 0x80000
	s_addc_u32 s31, s73, 0
	s_add_i32 s71, s86, s29
	global_load_lds_dwordx4 v180, s[72:73]
	s_mov_b32 m0, s71
	s_nop 0
	global_load_lds_dwordx4 v184, s[30:31]
	s_add_i32 m0, s71, 0x2000
	s_nop 0
	global_load_lds_dwordx4 v180, s[30:31]
	s_mov_b32 m0, s77
	s_nop 0
	global_load_lds_dwordx4 v186, s[74:75]
	s_mov_b32 m0, s78
	s_nop 0
	global_load_lds_dwordx4 v182, s[74:75]
	s_waitcnt vmcnt(8)
	s_waitcnt lgkmcnt(0)
	s_barrier
	s_waitcnt lgkmcnt(0)
	v_mfma_f32_16x16x32_bf16 v[92:95], v[118:121], v[154:157], v[92:95]
	v_mfma_f32_16x16x32_bf16 v[28:31], v[130:133], v[154:157], v[28:31]
	v_mfma_f32_16x16x32_bf16 v[84:87], v[118:121], v[170:173], v[84:87]
	v_mfma_f32_16x16x32_bf16 v[20:23], v[130:133], v[170:173], v[20:23]
	v_mfma_f32_16x16x32_bf16 v[76:79], v[118:121], v[204:207], v[76:79]
	v_mfma_f32_16x16x32_bf16 v[12:15], v[130:133], v[204:207], v[12:15]
	v_mfma_f32_16x16x32_bf16 v[72:75], v[118:121], v[226:229], v[72:75]
	v_mfma_f32_16x16x32_bf16 v[8:11], v[130:133], v[226:229], v[8:11]
	v_mfma_f32_16x16x32_bf16 v[92:95], v[126:129], v[166:169], v[92:95]
	v_mfma_f32_16x16x32_bf16 v[28:31], v[134:137], v[166:169], v[28:31]
	v_mfma_f32_16x16x32_bf16 v[84:87], v[126:129], v[174:177], v[84:87]
	v_mfma_f32_16x16x32_bf16 v[20:23], v[134:137], v[174:177], v[20:23]
	v_mfma_f32_16x16x32_bf16 v[76:79], v[126:129], v[208:211], v[76:79]
	v_mfma_f32_16x16x32_bf16 v[12:15], v[134:137], v[208:211], v[12:15]
	v_mfma_f32_16x16x32_bf16 v[72:75], v[126:129], v[230:233], v[72:75]
	v_mfma_f32_16x16x32_bf16 v[8:11], v[134:137], v[230:233], v[8:11]
	v_mfma_f32_16x16x32_bf16 v[88:91], v[138:141], v[154:157], v[88:91]
	v_mfma_f32_16x16x32_bf16 v[24:27], v[146:149], v[154:157], v[24:27]
	v_mfma_f32_16x16x32_bf16 v[80:83], v[138:141], v[170:173], v[80:83]
	v_mfma_f32_16x16x32_bf16 v[16:19], v[146:149], v[170:173], v[16:19]
	v_mfma_f32_16x16x32_bf16 v[68:71], v[138:141], v[204:207], v[68:71]
	v_mfma_f32_16x16x32_bf16 v[4:7], v[146:149], v[204:207], v[4:7]
	v_mfma_f32_16x16x32_bf16 v[64:67], v[138:141], v[226:229], v[64:67]
	v_mfma_f32_16x16x32_bf16 v[0:3], v[146:149], v[226:229], v[0:3]
	v_mfma_f32_16x16x32_bf16 v[88:91], v[142:145], v[166:169], v[88:91]
	v_mfma_f32_16x16x32_bf16 v[24:27], v[150:153], v[166:169], v[24:27]
	v_mfma_f32_16x16x32_bf16 v[80:83], v[142:145], v[174:177], v[80:83]
	v_mfma_f32_16x16x32_bf16 v[16:19], v[150:153], v[174:177], v[16:19]
	v_mfma_f32_16x16x32_bf16 v[68:71], v[142:145], v[208:211], v[68:71]
	v_mfma_f32_16x16x32_bf16 v[4:7], v[150:153], v[208:211], v[4:7]
	v_mfma_f32_16x16x32_bf16 v[64:67], v[142:145], v[230:233], v[64:67]
	v_mfma_f32_16x16x32_bf16 v[0:3], v[150:153], v[230:233], v[0:3]
	s_barrier
; #define PG8_STAGE(bufoff, gbase, voff) do { _Pragma("unroll") for (int _i = 0; _i < 2; ++_i) \
;         __builtin_amdgcn_global_load_lds((const unsigned*)((const char*)(gbase) + (voff)[_i]), (PG8_LAS unsigned*)(lds + (bufoff) + ldsw + _i * 8192), 16, 0, 0); } while (0)
; #define PG8_LDA(dst, b, h) do { _Pragma("unroll") for (int m = 0; m < 4; ++m) _Pragma("unroll") for (int k = 0; k < 2; ++k) dst[m][k] = *(const PG8_LAS bf16x8*)(lds + PG8_SA(b, h) + aoff + m * 2048 + k * 1024); } while (0)
; #define PG8_LDB(dst, b, h) do { _Pragma("unroll") for (int n = 0; n < 2; ++n) _Pragma("unroll") for (int k = 0; k < 2; ++k) dst[n][k] = *(const PG8_LAS bf16x8*)(lds + PG8_SB(b, h) + boff + n * 2048 + k * 1024); } while (0)
; template <class Epi, class Sched, bool ALIGN_EPI = false, bool SP2 = false>
; __device__ __forceinline__ void gemm_phase(PG8_LAS unsigned char* lds, const Gemm g, const Sched& S, const Epi& E) {
;     ...
;         for (int t = 0; t < nt; t += 2) {
;             const bool last = (t == nt - 2);
;             const char* a1 = cA + (size_t)(t + 1) * kstep;
;             const char* a2 = last ? nA : cA + (size_t)(t + 2) * kstep; const char* b2 = last ? nB : cB + (size_t)(t + 2) * kstep;
;             const char* a3 = a2 + kstep; const char* b3 = b2 + kstep;
;             if (last && has_next) S.a_ready(nxt);
;             if constexpr (SP2) {
;             PG8_LDB(B0, 0, 0); PG8_LDB(B1, 0, 1); PG8_SCHED; PG8_LDA(At, 0, 0); PG8_STAGE(PG8_SA(1, 1), a1 + hstep, voffA);
;             PG8_WAIT_V(8); PG8_WAIT_L(0); PG8_BAR; PG8_MMA(0, 0, At, B0); PG8_MMA(0, 1, At, B1); PG8_BAR; PG8_SCHED;
;             PG8_LDA(At, 0, 1); PG8_STAGE(PG8_SB(0, 0), b2, voffB); PG8_STAGE(PG8_SB(0, 1), b2 + hstep, voffB); PG8_STAGE(PG8_SA(0, 0), a2, voffA);
;             PG8_WAIT_V(8); PG8_WAIT_L(0); PG8_BAR; PG8_MMA(1, 0, At, B0); PG8_MMA(1, 1, At, B1); PG8_BAR; PG8_SCHED;
;             PG8_LDB(B0, 1, 0); PG8_LDB(B1, 1, 1); PG8_SCHED; PG8_LDA(At, 1, 0); PG8_STAGE(PG8_SA(0, 1), a2 + hstep, voffA);
;             PG8_WAIT_V(8); PG8_WAIT_L(0); PG8_BAR; PG8_MMA(0, 0, At, B0); PG8_MMA(0, 1, At, B1); PG8_BAR; PG8_SCHED;
;             PG8_LDA(At, 1, 1); PG8_STAGE(PG8_SB(1, 0), b3, voffB); PG8_STAGE(PG8_SB(1, 1), b3 + hstep, voffB); PG8_STAGE(PG8_SA(1, 0), a3, voffA);
;             PG8_WAIT_V(8); PG8_WAIT_L(0); PG8_BAR; PG8_MMA(1, 0, At, B0); PG8_MMA(1, 1, At, B1); PG8_BAR; PG8_SCHED;
	s_add_i32 s71, 0, 0x18000
	v_add_u32_e32 v116, s71, v213
	s_add_i32 s88, 0, 0x1c000
	ds_read_b128 v[118:121], v116
	ds_read_b128 v[126:129], v116 offset:1024
	ds_read_b128 v[130:133], v116 offset:2048
	ds_read_b128 v[134:137], v116 offset:3072
	v_add_u32_e32 v116, s88, v213
	ds_read_b128 v[138:141], v116
	ds_read_b128 v[142:145], v116 offset:1024
	ds_read_b128 v[146:149], v116 offset:2048
	ds_read_b128 v[150:153], v116 offset:3072
	s_add_u32 s30, s74, 0x80000
	s_addc_u32 s31, s75, 0
	s_mov_b32 m0, s79
	ds_read_b128 v[154:157], v219 offset:32768
	ds_read_b128 v[166:169], v219 offset:33792
	ds_read_b128 v[170:173], v219 offset:34816
	ds_read_b128 v[174:177], v219 offset:35840
	ds_read_b128 v[204:207], v219 offset:36864
	ds_read_b128 v[208:211], v219 offset:37888
	ds_read_b128 v[226:229], v219 offset:38912
	ds_read_b128 v[230:233], v219 offset:39936
	global_load_lds_dwordx4 v186, s[30:31]
	s_mov_b32 m0, s80
	s_nop 0
	global_load_lds_dwordx4 v182, s[30:31]
	s_waitcnt vmcnt(8)
	s_waitcnt lgkmcnt(0)
	s_barrier
	s_waitcnt lgkmcnt(0)
	v_mfma_f32_16x16x32_bf16 v[162:165], v[118:121], v[154:157], v[162:165]
	v_mfma_f32_16x16x32_bf16 v[60:63], v[130:133], v[154:157], v[60:63]
	v_mfma_f32_16x16x32_bf16 v[122:125], v[118:121], v[170:173], v[122:125]
	v_mfma_f32_16x16x32_bf16 v[52:55], v[130:133], v[170:173], v[52:55]
	v_mfma_f32_16x16x32_bf16 v[108:111], v[118:121], v[204:207], v[108:111]
	v_mfma_f32_16x16x32_bf16 v[44:47], v[130:133], v[204:207], v[44:47]
	v_mfma_f32_16x16x32_bf16 v[104:107], v[118:121], v[226:229], v[104:107]
	v_mfma_f32_16x16x32_bf16 v[40:43], v[130:133], v[226:229], v[40:43]
	v_mfma_f32_16x16x32_bf16 v[162:165], v[126:129], v[166:169], v[162:165]
	v_mfma_f32_16x16x32_bf16 v[60:63], v[134:137], v[166:169], v[60:63]
	v_mfma_f32_16x16x32_bf16 v[122:125], v[126:129], v[174:177], v[122:125]
	v_mfma_f32_16x16x32_bf16 v[52:55], v[134:137], v[174:177], v[52:55]
	v_mfma_f32_16x16x32_bf16 v[108:111], v[126:129], v[208:211], v[108:111]
	v_mfma_f32_16x16x32_bf16 v[44:47], v[134:137], v[208:211], v[44:47]
	v_mfma_f32_16x16x32_bf16 v[104:107], v[126:129], v[230:233], v[104:107]
	v_mfma_f32_16x16x32_bf16 v[40:43], v[134:137], v[230:233], v[40:43]
	v_mfma_f32_16x16x32_bf16 v[158:161], v[138:141], v[154:157], v[158:161]
	v_mfma_f32_16x16x32_bf16 v[56:59], v[146:149], v[154:157], v[56:59]
	v_mfma_f32_16x16x32_bf16 v[112:115], v[138:141], v[170:173], v[112:115]
	v_mfma_f32_16x16x32_bf16 v[48:51], v[146:149], v[170:173], v[48:51]
	v_mfma_f32_16x16x32_bf16 v[100:103], v[138:141], v[204:207], v[100:103]
	v_mfma_f32_16x16x32_bf16 v[36:39], v[146:149], v[204:207], v[36:39]
	v_mfma_f32_16x16x32_bf16 v[96:99], v[138:141], v[226:229], v[96:99]
	v_mfma_f32_16x16x32_bf16 v[32:35], v[146:149], v[226:229], v[32:35]
	v_mfma_f32_16x16x32_bf16 v[158:161], v[142:145], v[166:169], v[158:161]
	v_mfma_f32_16x16x32_bf16 v[56:59], v[150:153], v[166:169], v[56:59]
	v_mfma_f32_16x16x32_bf16 v[114:117], v[142:145], v[174:177], v[112:115]
	v_mfma_f32_16x16x32_bf16 v[48:51], v[150:153], v[174:177], v[48:51]
	v_mfma_f32_16x16x32_bf16 v[100:103], v[142:145], v[208:211], v[100:103]
	v_mfma_f32_16x16x32_bf16 v[36:39], v[150:153], v[208:211], v[36:39]
	v_mfma_f32_16x16x32_bf16 v[96:99], v[142:145], v[230:233], v[96:99]
	v_mfma_f32_16x16x32_bf16 v[32:35], v[150:153], v[230:233], v[32:35]
	s_barrier
	s_add_i32 s30, s71, s29
	s_mov_b32 m0, s30
	ds_read_b128 v[154:157], v219 offset:49152
	ds_read_b128 v[166:169], v219 offset:50176
	ds_read_b128 v[170:173], v219 offset:51200
	ds_read_b128 v[174:177], v219 offset:52224
	ds_read_b128 v[204:207], v219 offset:53248
	ds_read_b128 v[208:211], v219 offset:54272
	ds_read_b128 v[226:229], v219 offset:55296
	ds_read_b128 v[230:233], v219 offset:56320
	s_add_u32 s52, s72, 0x80
	s_addc_u32 s53, s73, 0
	global_load_lds_dwordx4 v184, s[52:53]
	s_add_i32 m0, s30, 0x2000
	s_add_u32 s30, s72, 0x80080
	s_addc_u32 s31, s73, 0
	s_add_i32 s71, s88, s29
	global_load_lds_dwordx4 v180, s[52:53]
	s_mov_b32 m0, s71
	s_nop 0
	global_load_lds_dwordx4 v184, s[30:31]
	s_add_i32 m0, s71, 0x2000
	s_nop 0
	global_load_lds_dwordx4 v180, s[30:31]
	s_mov_b32 m0, s83
	s_nop 0
	s_add_u32 s52, s74, 0x80
	s_addc_u32 s53, s75, 0
	global_load_lds_dwordx4 v186, s[52:53]
	s_mov_b32 m0, s84
	s_nop 0
	global_load_lds_dwordx4 v182, s[52:53]
	s_waitcnt vmcnt(8)
	s_waitcnt lgkmcnt(0)
	s_barrier
	s_waitcnt lgkmcnt(0)
	v_mfma_f32_16x16x32_bf16 v[92:95], v[118:121], v[154:157], v[92:95]
	v_mfma_f32_16x16x32_bf16 v[28:31], v[130:133], v[154:157], v[28:31]
	v_mfma_f32_16x16x32_bf16 v[84:87], v[118:121], v[170:173], v[84:87]
	v_mfma_f32_16x16x32_bf16 v[20:23], v[130:133], v[170:173], v[20:23]
	v_mfma_f32_16x16x32_bf16 v[76:79], v[118:121], v[204:207], v[76:79]
	v_mfma_f32_16x16x32_bf16 v[12:15], v[130:133], v[204:207], v[12:15]
	v_mfma_f32_16x16x32_bf16 v[72:75], v[118:121], v[226:229], v[72:75]
	v_mfma_f32_16x16x32_bf16 v[8:11], v[130:133], v[226:229], v[8:11]
	v_mfma_f32_16x16x32_bf16 v[92:95], v[126:129], v[166:169], v[92:95]
	v_mfma_f32_16x16x32_bf16 v[28:31], v[134:137], v[166:169], v[28:31]
	v_mfma_f32_16x16x32_bf16 v[84:87], v[126:129], v[174:177], v[84:87]
	v_mfma_f32_16x16x32_bf16 v[20:23], v[134:137], v[174:177], v[20:23]
	v_mfma_f32_16x16x32_bf16 v[76:79], v[126:129], v[208:211], v[76:79]
	v_mfma_f32_16x16x32_bf16 v[12:15], v[134:137], v[208:211], v[12:15]
	v_mfma_f32_16x16x32_bf16 v[72:75], v[126:129], v[230:233], v[72:75]
	v_mfma_f32_16x16x32_bf16 v[8:11], v[134:137], v[230:233], v[8:11]
	v_mfma_f32_16x16x32_bf16 v[88:91], v[138:141], v[154:157], v[88:91]
	v_mfma_f32_16x16x32_bf16 v[24:27], v[146:149], v[154:157], v[24:27]
	v_mfma_f32_16x16x32_bf16 v[80:83], v[138:141], v[170:173], v[80:83]
	v_mfma_f32_16x16x32_bf16 v[16:19], v[146:149], v[170:173], v[16:19]
	v_mfma_f32_16x16x32_bf16 v[68:71], v[138:141], v[204:207], v[68:71]
	v_mfma_f32_16x16x32_bf16 v[4:7], v[146:149], v[204:207], v[4:7]
	v_mfma_f32_16x16x32_bf16 v[64:67], v[138:141], v[226:229], v[64:67]
	v_mfma_f32_16x16x32_bf16 v[0:3], v[146:149], v[226:229], v[0:3]
	v_mfma_f32_16x16x32_bf16 v[88:91], v[142:145], v[166:169], v[88:91]
	v_mfma_f32_16x16x32_bf16 v[24:27], v[150:153], v[166:169], v[24:27]
	v_mfma_f32_16x16x32_bf16 v[80:83], v[142:145], v[174:177], v[80:83]
	v_mfma_f32_16x16x32_bf16 v[16:19], v[150:153], v[174:177], v[16:19]
	v_mfma_f32_16x16x32_bf16 v[68:71], v[142:145], v[208:211], v[68:71]
	v_mfma_f32_16x16x32_bf16 v[4:7], v[150:153], v[208:211], v[4:7]
	v_mfma_f32_16x16x32_bf16 v[64:67], v[142:145], v[230:233], v[64:67]
	v_mfma_f32_16x16x32_bf16 v[0:3], v[150:153], v[230:233], v[0:3]
	s_add_i32 s65, s65, 2
	s_add_u32 s10, s10, 0x100
	s_addc_u32 s11, s11, 0
	s_add_u32 s47, s47, 0x100
	s_addc_u32 s63, s63, 0
	s_cmp_gt_u32 s65, 29
	s_barrier
	s_cbranch_scc0 .LBB0_404
	s_and_b64 vcc, exec, s[54:55]
	s_cbranch_vccz .LBB0_407
	s_barrier

; #define PG8_STAGE(bufoff, gbase, voff) do { _Pragma("unroll") for (int _i = 0; _i < 2; ++_i) \
;         __builtin_amdgcn_global_load_lds((const unsigned*)((const char*)(gbase) + (voff)[_i]), (PG8_LAS unsigned*)(lds + (bufoff) + ldsw + _i * 8192), 16, 0, 0); } while (0)
; #define PG8_LDA(dst, b, h) do { _Pragma("unroll") for (int m = 0; m < 4; ++m) _Pragma("unroll") for (int k = 0; k < 2; ++k) dst[m][k] = *(const PG8_LAS bf16x8*)(lds + PG8_SA(b, h) + aoff + m * 2048 + k * 1024); } while (0)
; #define PG8_LDB(dst, b, h) do { _Pragma("unroll") for (int n = 0; n < 2; ++n) _Pragma("unroll") for (int k = 0; k < 2; ++k) dst[n][k] = *(const PG8_LAS bf16x8*)(lds + PG8_SB(b, h) + boff + n * 2048 + k * 1024); } while (0)
; #define PG8_MMA(ai, bj, At, Bt) do { __builtin_amdgcn_s_setprio(1); _Pragma("unroll") for (int m = 0; m < 4; ++m) _Pragma("unroll") for (int n = 0; n < 2; ++n) _Pragma("unroll") for (int k = 0; k < 2; ++k) \
;         acc[ai][bj][m][n] = __builtin_amdgcn_mfma_f32_16x16x32_bf16(Bt[n][k], At[m][k], acc[ai][bj][m][n], 0, 0, 0); __builtin_amdgcn_s_setprio(0); } while (0)
; #define PG8_WAIT_V(n) asm volatile("s_waitcnt vmcnt(" #n ")" ::: "memory")
; #define PG8_WAIT_L(n) asm volatile("s_waitcnt lgkmcnt(" #n ")" ::: "memory")
; template <class Epi, class Sched, bool ALIGN_EPI = false, bool SP2 = false>
; __device__ __forceinline__ void gemm_phase(PG8_LAS unsigned char* lds, const Gemm g, const Sched& S, const Epi& E) {
;     ...
;             const bool last = (t == nt - 2);
;             const char* a1 = cA + (size_t)(t + 1) * kstep;
;             const char* a2 = last ? nA : cA + (size_t)(t + 2) * kstep; const char* b2 = last ? nB : cB + (size_t)(t + 2) * kstep;
;             const char* a3 = a2 + kstep; const char* b3 = b2 + kstep;
;             if (last && has_next) S.a_ready(nxt);
;             if constexpr (SP2) {
;             PG8_LDB(B0, 0, 0); PG8_LDB(B1, 0, 1); PG8_SCHED; PG8_LDA(At, 0, 0); PG8_STAGE(PG8_SA(1, 1), a1 + hstep, voffA);
;             PG8_WAIT_V(8); PG8_WAIT_L(0); PG8_BAR; PG8_MMA(0, 0, At, B0); PG8_MMA(0, 1, At, B1); PG8_BAR; PG8_SCHED;
;             PG8_LDA(At, 0, 1); PG8_STAGE(PG8_SB(0, 0), b2, voffB); PG8_STAGE(PG8_SB(0, 1), b2 + hstep, voffB); PG8_STAGE(PG8_SA(0, 0), a2, voffA);
;             PG8_WAIT_V(8); PG8_WAIT_L(0); PG8_BAR; PG8_MMA(1, 0, At, B0); PG8_MMA(1, 1, At, B1); PG8_BAR; PG8_SCHED;
.LBB0_552:
	ds_read_b128 v[152:155], v149
	ds_read_b128 v[156:159], v149 offset:1024
	ds_read_b128 v[160:163], v149 offset:2048
	ds_read_b128 v[164:167], v149 offset:3072
	ds_read_b128 v[168:171], v150
	ds_read_b128 v[172:175], v150 offset:1024
	ds_read_b128 v[180:183], v150 offset:2048
	ds_read_b128 v[184:187], v150 offset:3072
	s_add_u32 s34, s26, 0x100
	s_addc_u32 s35, s27, 0
	s_cmpk_eq_i32 s67, 0x54
	s_cselect_b32 s45, s7, s35
	s_cselect_b32 s44, s6, s34
	s_cselect_b32 s37, s9, s66
	s_cselect_b32 s36, s8, s65
	s_add_i32 m0, s29, 0xc000
	ds_read_b128 v[188:191], v151
	ds_read_b128 v[192:195], v151 offset:1024
	ds_read_b128 v[196:199], v151 offset:2048
	ds_read_b128 v[200:203], v151 offset:3072
	ds_read_b128 v[204:207], v151 offset:4096
	ds_read_b128 v[208:211], v151 offset:5120
	ds_read_b128 v[212:215], v151 offset:6144
	ds_read_b128 v[216:219], v151 offset:7168
	global_load_lds_dwordx4 v136, s[26:27]
	s_add_i32 m0, s29, 0xe000
	s_nop 0
	global_load_lds_dwordx4 v138, s[26:27]
	s_waitcnt vmcnt(8)
	s_waitcnt lgkmcnt(0)
	s_barrier
	s_waitcnt lgkmcnt(0)
	v_mfma_f32_16x16x32_bf16 v[124:127], v[152:155], v[188:191], v[124:127]
	v_mfma_f32_16x16x32_bf16 v[120:123], v[160:163], v[188:191], v[120:123]
	v_mfma_f32_16x16x32_bf16 v[116:119], v[152:155], v[196:199], v[116:119]
	v_mfma_f32_16x16x32_bf16 v[108:111], v[160:163], v[196:199], v[108:111]
	v_mfma_f32_16x16x32_bf16 v[100:103], v[152:155], v[204:207], v[100:103]
	v_mfma_f32_16x16x32_bf16 v[92:95], v[160:163], v[204:207], v[92:95]
	v_mfma_f32_16x16x32_bf16 v[84:87], v[152:155], v[212:215], v[84:87]
	v_mfma_f32_16x16x32_bf16 v[76:79], v[160:163], v[212:215], v[76:79]
	v_mfma_f32_16x16x32_bf16 v[124:127], v[156:159], v[192:195], v[124:127]
	v_mfma_f32_16x16x32_bf16 v[120:123], v[164:167], v[192:195], v[120:123]
	v_mfma_f32_16x16x32_bf16 v[116:119], v[156:159], v[200:203], v[116:119]
	v_mfma_f32_16x16x32_bf16 v[108:111], v[164:167], v[200:203], v[108:111]
	v_mfma_f32_16x16x32_bf16 v[100:103], v[156:159], v[208:211], v[100:103]
	v_mfma_f32_16x16x32_bf16 v[92:95], v[164:167], v[208:211], v[92:95]
	v_mfma_f32_16x16x32_bf16 v[84:87], v[156:159], v[216:219], v[84:87]
	v_mfma_f32_16x16x32_bf16 v[76:79], v[164:167], v[216:219], v[76:79]
	v_mfma_f32_16x16x32_bf16 v[112:115], v[168:171], v[188:191], v[112:115]
	v_mfma_f32_16x16x32_bf16 v[104:107], v[180:183], v[188:191], v[104:107]
	v_mfma_f32_16x16x32_bf16 v[96:99], v[168:171], v[196:199], v[96:99]
	v_mfma_f32_16x16x32_bf16 v[88:91], v[180:183], v[196:199], v[88:91]
	v_mfma_f32_16x16x32_bf16 v[80:83], v[168:171], v[204:207], v[80:83]
	v_mfma_f32_16x16x32_bf16 v[72:75], v[180:183], v[204:207], v[72:75]
	v_mfma_f32_16x16x32_bf16 v[68:71], v[168:171], v[212:215], v[68:71]
	v_mfma_f32_16x16x32_bf16 v[64:67], v[180:183], v[212:215], v[64:67]
	v_mfma_f32_16x16x32_bf16 v[112:115], v[172:175], v[192:195], v[112:115]
	v_mfma_f32_16x16x32_bf16 v[104:107], v[184:187], v[192:195], v[104:107]
	v_mfma_f32_16x16x32_bf16 v[96:99], v[172:175], v[200:203], v[96:99]
	v_mfma_f32_16x16x32_bf16 v[88:91], v[184:187], v[200:203], v[88:91]
	v_mfma_f32_16x16x32_bf16 v[80:83], v[172:175], v[208:211], v[80:83]
	v_mfma_f32_16x16x32_bf16 v[72:75], v[184:187], v[208:211], v[72:75]
	v_mfma_f32_16x16x32_bf16 v[68:71], v[172:175], v[216:219], v[68:71]
	v_mfma_f32_16x16x32_bf16 v[64:67], v[184:187], v[216:219], v[64:67]
	s_barrier
	s_add_i32 s26, s55, s1
	s_mov_b32 m0, s26
	ds_read_b128 v[188:191], v151 offset:16384
	ds_read_b128 v[192:195], v151 offset:17408
	ds_read_b128 v[196:199], v151 offset:18432
	ds_read_b128 v[200:203], v151 offset:19456
	ds_read_b128 v[204:207], v151 offset:20480
	ds_read_b128 v[208:211], v151 offset:21504
	ds_read_b128 v[212:215], v151 offset:22528
	ds_read_b128 v[216:219], v151 offset:23552
	global_load_lds_dwordx4 v130, s[36:37]
	s_add_i32 m0, s26, 0x2000
	s_add_u32 s26, s36, 0x160000
	s_addc_u32 s27, s37, 0
	s_add_i32 s30, s56, s1
	global_load_lds_dwordx4 v134, s[36:37]
	s_mov_b32 m0, s30
	s_nop 0
	global_load_lds_dwordx4 v130, s[26:27]
	s_add_i32 m0, s30, 0x2000
	s_nop 0
	global_load_lds_dwordx4 v134, s[26:27]
	s_mov_b32 m0, s29
	s_nop 0
	global_load_lds_dwordx4 v128, s[44:45]
	s_mov_b32 m0, s33
	s_nop 0
	global_load_lds_dwordx4 v132, s[44:45]
	s_waitcnt vmcnt(8)
	s_waitcnt lgkmcnt(0)
	s_barrier
	s_waitcnt lgkmcnt(0)
	v_mfma_f32_16x16x32_bf16 v[60:63], v[152:155], v[188:191], v[60:63]
	v_mfma_f32_16x16x32_bf16 v[56:59], v[160:163], v[188:191], v[56:59]
	v_mfma_f32_16x16x32_bf16 v[52:55], v[152:155], v[196:199], v[52:55]
	v_mfma_f32_16x16x32_bf16 v[44:47], v[160:163], v[196:199], v[44:47]
	v_mfma_f32_16x16x32_bf16 v[36:39], v[152:155], v[204:207], v[36:39]
	v_mfma_f32_16x16x32_bf16 v[28:31], v[160:163], v[204:207], v[28:31]
	v_mfma_f32_16x16x32_bf16 v[20:23], v[152:155], v[212:215], v[20:23]
	v_mfma_f32_16x16x32_bf16 v[12:15], v[160:163], v[212:215], v[12:15]
	v_mfma_f32_16x16x32_bf16 v[60:63], v[156:159], v[192:195], v[60:63]
	v_mfma_f32_16x16x32_bf16 v[56:59], v[164:167], v[192:195], v[56:59]
	v_mfma_f32_16x16x32_bf16 v[52:55], v[156:159], v[200:203], v[52:55]
	v_mfma_f32_16x16x32_bf16 v[44:47], v[164:167], v[200:203], v[44:47]
	v_mfma_f32_16x16x32_bf16 v[36:39], v[156:159], v[208:211], v[36:39]
	v_mfma_f32_16x16x32_bf16 v[28:31], v[164:167], v[208:211], v[28:31]
	v_mfma_f32_16x16x32_bf16 v[20:23], v[156:159], v[216:219], v[20:23]
	v_mfma_f32_16x16x32_bf16 v[12:15], v[164:167], v[216:219], v[12:15]
	v_mfma_f32_16x16x32_bf16 v[48:51], v[168:171], v[188:191], v[48:51]
	v_mfma_f32_16x16x32_bf16 v[40:43], v[180:183], v[188:191], v[40:43]
	v_mfma_f32_16x16x32_bf16 v[32:35], v[168:171], v[196:199], v[32:35]
	v_mfma_f32_16x16x32_bf16 v[24:27], v[180:183], v[196:199], v[24:27]
	v_mfma_f32_16x16x32_bf16 v[16:19], v[168:171], v[204:207], v[16:19]
	v_mfma_f32_16x16x32_bf16 v[8:11], v[180:183], v[204:207], v[8:11]
	v_mfma_f32_16x16x32_bf16 v[4:7], v[168:171], v[212:215], v[4:7]
	v_mfma_f32_16x16x32_bf16 v[0:3], v[180:183], v[212:215], v[0:3]
	v_mfma_f32_16x16x32_bf16 v[48:51], v[172:175], v[192:195], v[48:51]
	v_mfma_f32_16x16x32_bf16 v[40:43], v[184:187], v[192:195], v[40:43]
	v_mfma_f32_16x16x32_bf16 v[32:35], v[172:175], v[200:203], v[32:35]
	v_mfma_f32_16x16x32_bf16 v[24:27], v[184:187], v[200:203], v[24:27]
	v_mfma_f32_16x16x32_bf16 v[16:19], v[172:175], v[208:211], v[16:19]
	v_mfma_f32_16x16x32_bf16 v[8:11], v[184:187], v[208:211], v[8:11]
	v_mfma_f32_16x16x32_bf16 v[4:7], v[172:175], v[216:219], v[4:7]
	v_mfma_f32_16x16x32_bf16 v[0:3], v[184:187], v[216:219], v[0:3]
	s_barrier
; #define PG8_STAGE(bufoff, gbase, voff) do { _Pragma("unroll") for (int _i = 0; _i < 2; ++_i) \
;         __builtin_amdgcn_global_load_lds((const unsigned*)((const char*)(gbase) + (voff)[_i]), (PG8_LAS unsigned*)(lds + (bufoff) + ldsw + _i * 8192), 16, 0, 0); } while (0)
; #define PG8_LDA(dst, b, h) do { _Pragma("unroll") for (int m = 0; m < 4; ++m) _Pragma("unroll") for (int k = 0; k < 2; ++k) dst[m][k] = *(const PG8_LAS bf16x8*)(lds + PG8_SA(b, h) + aoff + m * 2048 + k * 1024); } while (0)
; #define PG8_LDB(dst, b, h) do { _Pragma("unroll") for (int n = 0; n < 2; ++n) _Pragma("unroll") for (int k = 0; k < 2; ++k) dst[n][k] = *(const PG8_LAS bf16x8*)(lds + PG8_SB(b, h) + boff + n * 2048 + k * 1024); } while (0)
; #define PG8_MMA(ai, bj, At, Bt) do { __builtin_amdgcn_s_setprio(1); _Pragma("unroll") for (int m = 0; m < 4; ++m) _Pragma("unroll") for (int n = 0; n < 2; ++n) _Pragma("unroll") for (int k = 0; k < 2; ++k) \
;         acc[ai][bj][m][n] = __builtin_amdgcn_mfma_f32_16x16x32_bf16(Bt[n][k], At[m][k], acc[ai][bj][m][n], 0, 0, 0); __builtin_amdgcn_s_setprio(0); } while (0)
; #define PG8_WAIT_V(n) asm volatile("s_waitcnt vmcnt(" #n ")" ::: "memory")
; #define PG8_WAIT_L(n) asm volatile("s_waitcnt lgkmcnt(" #n ")" ::: "memory")
; #define PG8_BAR __builtin_amdgcn_s_barrier()
; #define PG8_SCHED __builtin_amdgcn_sched_barrier(0)
; template <class Epi, class Sched, bool ALIGN_EPI = false, bool SP2 = false>
; __device__ __forceinline__ void gemm_phase(PG8_LAS unsigned char* lds, const Gemm g, const Sched& S, const Epi& E) {
;     ...
;         for (int t = 0; t < nt; t += 2) {
;             const bool last = (t == nt - 2);
;             const char* a1 = cA + (size_t)(t + 1) * kstep;
;             const char* a2 = last ? nA : cA + (size_t)(t + 2) * kstep; const char* b2 = last ? nB : cB + (size_t)(t + 2) * kstep;
;     ...
;             PG8_LDB(B0, 1, 0); PG8_LDB(B1, 1, 1); PG8_SCHED; PG8_LDA(At, 1, 0); PG8_STAGE(PG8_SA(0, 1), a2 + hstep, voffA);
;             PG8_WAIT_V(8); PG8_WAIT_L(0); PG8_BAR; PG8_MMA(0, 0, At, B0); PG8_MMA(0, 1, At, B1); PG8_BAR; PG8_SCHED;
;             PG8_LDA(At, 1, 1); PG8_STAGE(PG8_SB(1, 0), b3, voffB); PG8_STAGE(PG8_SB(1, 1), b3 + hstep, voffB); PG8_STAGE(PG8_SA(1, 0), a3, voffA);
;             PG8_WAIT_V(8); PG8_WAIT_L(0); PG8_BAR; PG8_MMA(1, 0, At, B0); PG8_MMA(1, 1, At, B1); PG8_BAR; PG8_SCHED;
	s_add_i32 s30, 0, 0x18000
	s_add_i32 s31, 0, 0x1c000
	v_add_u32_e32 v164, s30, v147
	v_add_u32_e32 v184, s31, v147
	ds_read_b128 v[152:155], v164
	ds_read_b128 v[156:159], v164 offset:1024
	ds_read_b128 v[160:163], v164 offset:2048
	ds_read_b128 v[164:167], v164 offset:3072
	ds_read_b128 v[168:171], v184
	ds_read_b128 v[172:175], v184 offset:1024
	ds_read_b128 v[180:183], v184 offset:2048
	ds_read_b128 v[184:187], v184 offset:3072
	s_add_u32 s26, s44, 0x160000
	s_addc_u32 s27, s45, 0
	s_mov_b32 m0, s46
	ds_read_b128 v[188:191], v151 offset:32768
	ds_read_b128 v[192:195], v151 offset:33792
	ds_read_b128 v[196:199], v151 offset:34816
	ds_read_b128 v[200:203], v151 offset:35840
	ds_read_b128 v[204:207], v151 offset:36864
	ds_read_b128 v[208:211], v151 offset:37888
	ds_read_b128 v[212:215], v151 offset:38912
	ds_read_b128 v[216:219], v151 offset:39936
	global_load_lds_dwordx4 v128, s[26:27]
	s_mov_b32 m0, s47
	s_nop 0
	global_load_lds_dwordx4 v132, s[26:27]
	s_waitcnt vmcnt(8)
	s_waitcnt lgkmcnt(0)
	s_barrier
	s_waitcnt lgkmcnt(0)
	v_mfma_f32_16x16x32_bf16 v[124:127], v[152:155], v[188:191], v[124:127]
	v_mfma_f32_16x16x32_bf16 v[120:123], v[160:163], v[188:191], v[120:123]
	v_mfma_f32_16x16x32_bf16 v[116:119], v[152:155], v[196:199], v[116:119]
	v_mfma_f32_16x16x32_bf16 v[108:111], v[160:163], v[196:199], v[108:111]
	v_mfma_f32_16x16x32_bf16 v[100:103], v[152:155], v[204:207], v[100:103]
	v_mfma_f32_16x16x32_bf16 v[92:95], v[160:163], v[204:207], v[92:95]
	v_mfma_f32_16x16x32_bf16 v[84:87], v[152:155], v[212:215], v[84:87]
	v_mfma_f32_16x16x32_bf16 v[76:79], v[160:163], v[212:215], v[76:79]
	v_mfma_f32_16x16x32_bf16 v[124:127], v[156:159], v[192:195], v[124:127]
	v_mfma_f32_16x16x32_bf16 v[120:123], v[164:167], v[192:195], v[120:123]
	v_mfma_f32_16x16x32_bf16 v[116:119], v[156:159], v[200:203], v[116:119]
	v_mfma_f32_16x16x32_bf16 v[108:111], v[164:167], v[200:203], v[108:111]
	v_mfma_f32_16x16x32_bf16 v[100:103], v[156:159], v[208:211], v[100:103]
	v_mfma_f32_16x16x32_bf16 v[92:95], v[164:167], v[208:211], v[92:95]
	v_mfma_f32_16x16x32_bf16 v[84:87], v[156:159], v[216:219], v[84:87]
	v_mfma_f32_16x16x32_bf16 v[76:79], v[164:167], v[216:219], v[76:79]
	v_mfma_f32_16x16x32_bf16 v[112:115], v[168:171], v[188:191], v[112:115]
	v_mfma_f32_16x16x32_bf16 v[104:107], v[180:183], v[188:191], v[104:107]
	v_mfma_f32_16x16x32_bf16 v[96:99], v[168:171], v[196:199], v[96:99]
	v_mfma_f32_16x16x32_bf16 v[88:91], v[180:183], v[196:199], v[88:91]
	v_mfma_f32_16x16x32_bf16 v[80:83], v[168:171], v[204:207], v[80:83]
	v_mfma_f32_16x16x32_bf16 v[72:75], v[180:183], v[204:207], v[72:75]
	v_mfma_f32_16x16x32_bf16 v[68:71], v[168:171], v[212:215], v[68:71]
	v_mfma_f32_16x16x32_bf16 v[64:67], v[180:183], v[212:215], v[64:67]
	v_mfma_f32_16x16x32_bf16 v[112:115], v[172:175], v[192:195], v[112:115]
	v_mfma_f32_16x16x32_bf16 v[104:107], v[184:187], v[192:195], v[104:107]
	v_mfma_f32_16x16x32_bf16 v[96:99], v[172:175], v[200:203], v[96:99]
	v_mfma_f32_16x16x32_bf16 v[88:91], v[184:187], v[200:203], v[88:91]
	v_mfma_f32_16x16x32_bf16 v[80:83], v[172:175], v[208:211], v[80:83]
	v_mfma_f32_16x16x32_bf16 v[72:75], v[184:187], v[208:211], v[72:75]
	v_mfma_f32_16x16x32_bf16 v[68:71], v[172:175], v[216:219], v[68:71]
	v_mfma_f32_16x16x32_bf16 v[64:67], v[184:187], v[216:219], v[64:67]
	s_barrier
	s_add_i32 s26, s30, s1
	s_mov_b32 m0, s26
	ds_read_b128 v[188:191], v151 offset:49152
	ds_read_b128 v[192:195], v151 offset:50176
	ds_read_b128 v[196:199], v151 offset:51200
	ds_read_b128 v[200:203], v151 offset:52224
	ds_read_b128 v[204:207], v151 offset:53248
	ds_read_b128 v[208:211], v151 offset:54272
	ds_read_b128 v[212:215], v151 offset:55296
	ds_read_b128 v[216:219], v151 offset:56320
	s_add_u32 s10, s36, 0x80
	s_addc_u32 s11, s37, 0
	global_load_lds_dwordx4 v130, s[10:11]
	s_add_i32 m0, s26, 0x2000
	s_add_u32 s26, s36, 0x160080
	s_addc_u32 s27, s37, 0
	s_add_i32 s30, s31, s1
	global_load_lds_dwordx4 v134, s[10:11]
	s_mov_b32 m0, s30
	s_nop 0
	global_load_lds_dwordx4 v130, s[26:27]
	s_add_i32 m0, s30, 0x2000
	s_nop 0
	global_load_lds_dwordx4 v134, s[26:27]
	s_mov_b32 m0, s53
	s_nop 0
	s_add_u32 s10, s44, 0x80
	s_addc_u32 s11, s45, 0
	global_load_lds_dwordx4 v128, s[10:11]
	s_mov_b32 m0, s54
	s_nop 0
	global_load_lds_dwordx4 v132, s[10:11]
	s_waitcnt vmcnt(8)
	s_waitcnt lgkmcnt(0)
	s_barrier
	s_waitcnt lgkmcnt(0)
	v_mfma_f32_16x16x32_bf16 v[60:63], v[152:155], v[188:191], v[60:63]
	v_mfma_f32_16x16x32_bf16 v[56:59], v[160:163], v[188:191], v[56:59]
	v_mfma_f32_16x16x32_bf16 v[52:55], v[152:155], v[196:199], v[52:55]
	v_mfma_f32_16x16x32_bf16 v[44:47], v[160:163], v[196:199], v[44:47]
	v_mfma_f32_16x16x32_bf16 v[36:39], v[152:155], v[204:207], v[36:39]
	v_mfma_f32_16x16x32_bf16 v[28:31], v[160:163], v[204:207], v[28:31]
	v_mfma_f32_16x16x32_bf16 v[20:23], v[152:155], v[212:215], v[20:23]
	v_mfma_f32_16x16x32_bf16 v[12:15], v[160:163], v[212:215], v[12:15]
	v_mfma_f32_16x16x32_bf16 v[60:63], v[156:159], v[192:195], v[60:63]
	v_mfma_f32_16x16x32_bf16 v[56:59], v[164:167], v[192:195], v[56:59]
	v_mfma_f32_16x16x32_bf16 v[52:55], v[156:159], v[200:203], v[52:55]
	v_mfma_f32_16x16x32_bf16 v[44:47], v[164:167], v[200:203], v[44:47]
	v_mfma_f32_16x16x32_bf16 v[36:39], v[156:159], v[208:211], v[36:39]
	v_mfma_f32_16x16x32_bf16 v[28:31], v[164:167], v[208:211], v[28:31]
	v_mfma_f32_16x16x32_bf16 v[20:23], v[156:159], v[216:219], v[20:23]
	v_mfma_f32_16x16x32_bf16 v[12:15], v[164:167], v[216:219], v[12:15]
	v_mfma_f32_16x16x32_bf16 v[48:51], v[168:171], v[188:191], v[48:51]
	v_mfma_f32_16x16x32_bf16 v[40:43], v[180:183], v[188:191], v[40:43]
	v_mfma_f32_16x16x32_bf16 v[32:35], v[168:171], v[196:199], v[32:35]
	v_mfma_f32_16x16x32_bf16 v[24:27], v[180:183], v[196:199], v[24:27]
	v_mfma_f32_16x16x32_bf16 v[16:19], v[168:171], v[204:207], v[16:19]
	v_mfma_f32_16x16x32_bf16 v[8:11], v[180:183], v[204:207], v[8:11]
	v_mfma_f32_16x16x32_bf16 v[4:7], v[168:171], v[212:215], v[4:7]
	v_mfma_f32_16x16x32_bf16 v[0:3], v[180:183], v[212:215], v[0:3]
	v_mfma_f32_16x16x32_bf16 v[48:51], v[172:175], v[192:195], v[48:51]
	v_mfma_f32_16x16x32_bf16 v[40:43], v[184:187], v[192:195], v[40:43]
	v_mfma_f32_16x16x32_bf16 v[32:35], v[172:175], v[200:203], v[32:35]
	v_mfma_f32_16x16x32_bf16 v[24:27], v[184:187], v[200:203], v[24:27]
	v_mfma_f32_16x16x32_bf16 v[16:19], v[172:175], v[208:211], v[16:19]
	v_mfma_f32_16x16x32_bf16 v[8:11], v[184:187], v[208:211], v[8:11]
	v_mfma_f32_16x16x32_bf16 v[4:7], v[172:175], v[216:219], v[4:7]
	v_mfma_f32_16x16x32_bf16 v[0:3], v[184:187], v[216:219], v[0:3]
	s_add_i32 s67, s67, 2
	s_add_u32 s65, s65, 0x100
	s_addc_u32 s66, s66, 0
	s_mov_b64 s[26:27], s[34:35]
	s_cmpk_gt_u32 s67, 0x55
	s_barrier
; __device__ __forceinline__ unsigned cvt_pk_bf16(float lo, float hi) { unsigned r; asm volatile("v_cvt_pk_bf16_f32 %0, %1, %2" : "=v"(r) : "v"(lo), "v"(hi)); return r; }
; #define PG8_WAIT_V(n) asm volatile("s_waitcnt vmcnt(" #n ")" ::: "memory")
; #define PG8_BAR __builtin_amdgcn_s_barrier()
;     __device__ __forceinline__ void operator()(const f32x4 (&acc)[2][2][4][2], const Unit& u, int wr, int wc, int fr, int fq) const {
;         const int row0 = u.pm * BM + wr * 64 + fr; const int col0 = u.pn * BM + wc * 32 + 8 * fq;
; #pragma unroll
;         for (int ai = 0; ai < 2; ++ai)
; #pragma unroll
;             for (int m = 0; m < 4; ++m) { bf16_t* rowp = O + (size_t)(row0 + ai * HALF + m * 16) * ldc + col0;
; #pragma unroll
;                 for (int bj = 0; bj < 2; ++bj) { const f32x4 v0 = acc[ai][bj][m][0], v1 = acc[ai][bj][m][1];
;                     u32x4 w; w.x = cvt_pk_bf16(v0[0], v0[1]); w.y = cvt_pk_bf16(v0[2], v0[3]); w.z = cvt_pk_bf16(v1[0], v1[1]); w.w = cvt_pk_bf16(v1[2], v1[3]);
;                     *(u32x4*)(rowp + bj * HALF) = w; } }
; template <class Epi, class Sched, bool ALIGN_EPI = false, bool SP2 = false>
; __device__ __forceinline__ void gemm_phase(PG8_LAS unsigned char* lds, const Gemm g, const Sched& S, const Epi& E) {
;     ...
;         if constexpr (!Epi::AFTER_DRAIN) { E(acc, cur, wr, wc, fr, fq); S.done(cur); }
;         if (!has_next) break;
; #pragma unroll
;         for (int a = 0; a < 2; ++a)
; #pragma unroll
;             for (int b = 0; b < 2; ++b)
; #pragma unroll
;                 for (int m = 0; m < 4; ++m)
; #pragma unroll
;                     for (int n = 0; n < 2; ++n) acc[a][b][m][n] = (f32x4){0.f, 0.f, 0.f, 0.f};
;         cur = nxt; cA = nA; cB = nB; ++ui;
;         if constexpr (ALIGN_EPI) { if (wr == 1) PG8_BAR; }
;     }
;     PG8_WAIT_V(0);
;     if constexpr (!ALIGN_EPI) { if (wr == 0) PG8_BAR; }
	s_cbranch_scc0 .LBB0_552
	v_lshl_add_u32 v152, s63, 8, v146
	v_lshl_or_b32 v144, s64, 8, v148
	v_ashrrev_i32_e32 v153, 31, v152
	v_ashrrev_i32_e32 v145, 31, v144
	v_lshlrev_b64 v[154:155], 12, v[152:153]
	v_lshl_add_u64 v[154:155], s[90:91], 0, v[154:155]
	v_lshlrev_b64 v[156:157], 1, v[144:145]
	v_lshl_add_u64 v[144:145], v[154:155], 0, v[156:157]
	v_cvt_pk_bf16_f32 v124, v124, v125
	v_cvt_pk_bf16_f32 v125, v126, v127
	v_cvt_pk_bf16_f32 v126, v120, v121
	v_cvt_pk_bf16_f32 v127, v122, v123
	global_store_dwordx4 v[144:145], v[124:127], off
	v_cvt_pk_bf16_f32 v112, v112, v113
	v_cvt_pk_bf16_f32 v113, v114, v115
	v_cvt_pk_bf16_f32 v114, v104, v105
	v_or_b32_e32 v104, 16, v152
	v_ashrrev_i32_e32 v105, 31, v104
	v_lshlrev_b64 v[104:105], 12, v[104:105]
	v_lshl_add_u64 v[104:105], s[90:91], 0, v[104:105]
	v_cvt_pk_bf16_f32 v115, v106, v107
	global_store_dwordx4 v[144:145], v[112:115], off offset:256
	s_mov_b32 s64, s61
	s_mov_b32 s63, s62
	v_lshl_add_u64 v[112:113], v[104:105], 0, v[156:157]
	v_cvt_pk_bf16_f32 v104, v116, v117
	v_cvt_pk_bf16_f32 v105, v118, v119
	v_cvt_pk_bf16_f32 v106, v108, v109
	v_cvt_pk_bf16_f32 v107, v110, v111
	global_store_dwordx4 v[112:113], v[104:107], off
	v_cvt_pk_bf16_f32 v96, v96, v97
	v_cvt_pk_bf16_f32 v97, v98, v99
	v_cvt_pk_bf16_f32 v98, v88, v89
	v_or_b32_e32 v88, 32, v152
	v_ashrrev_i32_e32 v89, 31, v88
	v_lshlrev_b64 v[88:89], 12, v[88:89]
	v_lshl_add_u64 v[88:89], s[90:91], 0, v[88:89]
	v_cvt_pk_bf16_f32 v99, v90, v91
	global_store_dwordx4 v[112:113], v[96:99], off offset:256
	s_mov_b64 s[34:35], s[8:9]
	s_mov_b64 s[26:27], s[6:7]
	v_lshl_add_u64 v[96:97], v[88:89], 0, v[156:157]
	v_cvt_pk_bf16_f32 v88, v100, v101
	v_cvt_pk_bf16_f32 v89, v102, v103
	v_cvt_pk_bf16_f32 v90, v92, v93
	v_cvt_pk_bf16_f32 v91, v94, v95
	global_store_dwordx4 v[96:97], v[88:91], off
	v_cvt_pk_bf16_f32 v80, v80, v81
	v_cvt_pk_bf16_f32 v81, v82, v83
	v_cvt_pk_bf16_f32 v82, v72, v73
	v_or_b32_e32 v72, 48, v152
	v_ashrrev_i32_e32 v73, 31, v72
	v_lshlrev_b64 v[72:73], 12, v[72:73]
	v_lshl_add_u64 v[72:73], s[90:91], 0, v[72:73]
	v_cvt_pk_bf16_f32 v83, v74, v75
	global_store_dwordx4 v[96:97], v[80:83], off offset:256
	s_nop 1
	v_lshl_add_u64 v[80:81], v[72:73], 0, v[156:157]
	v_cvt_pk_bf16_f32 v72, v84, v85
	v_cvt_pk_bf16_f32 v73, v86, v87
	v_cvt_pk_bf16_f32 v74, v76, v77
	v_cvt_pk_bf16_f32 v75, v78, v79
	global_store_dwordx4 v[80:81], v[72:75], off
	v_cvt_pk_bf16_f32 v68, v68, v69
	v_cvt_pk_bf16_f32 v69, v70, v71
	v_cvt_pk_bf16_f32 v70, v64, v65
	v_cvt_pk_bf16_f32 v71, v66, v67
	global_store_dwordx4 v[80:81], v[68:71], off offset:256
	v_cvt_pk_bf16_f32 v60, v60, v61
	v_cvt_pk_bf16_f32 v61, v62, v63
	v_cvt_pk_bf16_f32 v62, v56, v57
	v_add_co_u32_e32 v56, vcc, s57, v144
	v_lshl_add_u64 v[64:65], v[144:145], 0, s[16:17]
	s_nop 0
	v_addc_co_u32_e32 v57, vcc, 0, v145, vcc
	v_cvt_pk_bf16_f32 v63, v58, v59
	global_store_dwordx4 v[56:57], v[60:63], off
	v_cvt_pk_bf16_f32 v48, v48, v49
	v_cvt_pk_bf16_f32 v49, v50, v51
	v_cvt_pk_bf16_f32 v50, v40, v41
	v_cvt_pk_bf16_f32 v51, v42, v43
	global_store_dwordx4 v[64:65], v[48:51], off offset:256
	v_cvt_pk_bf16_f32 v40, v52, v53
	v_cvt_pk_bf16_f32 v41, v54, v55
	v_cvt_pk_bf16_f32 v42, v44, v45
	v_add_co_u32_e32 v44, vcc, s58, v144
	s_nop 0
	v_lshl_add_u64 v[48:49], v[144:145], 0, s[20:21]
	v_addc_co_u32_e32 v45, vcc, 0, v145, vcc
	v_cvt_pk_bf16_f32 v43, v46, v47
	global_store_dwordx4 v[44:45], v[40:43], off
	v_cvt_pk_bf16_f32 v32, v32, v33
	v_cvt_pk_bf16_f32 v33, v34, v35
	v_cvt_pk_bf16_f32 v34, v24, v25
	v_cvt_pk_bf16_f32 v35, v26, v27
	global_store_dwordx4 v[48:49], v[32:35], off offset:256
	v_cvt_pk_bf16_f32 v24, v36, v37
	v_cvt_pk_bf16_f32 v25, v38, v39
	v_cvt_pk_bf16_f32 v26, v28, v29
	v_add_co_u32_e32 v28, vcc, s59, v144
	s_nop 0
	v_lshl_add_u64 v[32:33], v[144:145], 0, s[22:23]
	v_addc_co_u32_e32 v29, vcc, 0, v145, vcc
	v_cvt_pk_bf16_f32 v27, v30, v31
	global_store_dwordx4 v[28:29], v[24:27], off
	v_cvt_pk_bf16_f32 v16, v16, v17
	v_cvt_pk_bf16_f32 v17, v18, v19
	v_cvt_pk_bf16_f32 v18, v8, v9
	v_cvt_pk_bf16_f32 v19, v10, v11
	global_store_dwordx4 v[32:33], v[16:19], off offset:256
	v_cvt_pk_bf16_f32 v8, v20, v21
	v_cvt_pk_bf16_f32 v9, v22, v23
	v_cvt_pk_bf16_f32 v10, v12, v13
	v_add_co_u32_e32 v12, vcc, s60, v144
	s_nop 0
	v_lshl_add_u64 v[16:17], v[144:145], 0, s[24:25]
	v_addc_co_u32_e32 v13, vcc, 0, v145, vcc
	s_and_b64 vcc, exec, s[4:5]
	v_cvt_pk_bf16_f32 v11, v14, v15
	global_store_dwordx4 v[12:13], v[8:11], off
	v_cvt_pk_bf16_f32 v4, v4, v5
	v_cvt_pk_bf16_f32 v5, v6, v7
	v_cvt_pk_bf16_f32 v6, v0, v1
	v_cvt_pk_bf16_f32 v7, v2, v3
	global_store_dwordx4 v[16:17], v[4:7], off offset:256
	s_cbranch_vccz .LBB0_541
	s_waitcnt vmcnt(0)
	s_cmpk_gt_u32 s0, 0xff
	s_cbranch_scc1 .LBB0_556
	s_barrier
